# nt hint on the read-once loads of the deferred conversions (conv gate/up, w_out, w_down, cache V)
# speedup vs baseline: 1.0107x; 1.0107x over previous
.LBB0_65:
	s_mul_hi_i32 s46, s45, 0x2fa0be83
	s_lshr_b32 s47, s46, 31
	s_ashr_i32 s46, s46, 6
	s_add_i32 s84, s46, s47
	s_mul_i32 s46, s84, 0xffffd500
	s_mul_i32 s47, s84, 0xffffaa00
	s_add_i32 s46, s43, s46
	s_add_i32 s47, s44, s47
	s_and_b32 s48, s46, 0x60
	s_and_b32 s47, s47, 0xffffff00
	s_or_b32 s48, s48, s40
	s_mul_i32 s80, s84, 0x2b0000
	s_or_b32 s48, s48, s47
	s_mul_hi_i32 s49, s84, 0x2b0000
	s_add_u32 s80, s42, s80
	s_addc_u32 s49, s41, s49
	s_ashr_i32 s47, s46, 31
	s_lshl_b64 s[46:47], s[46:47], 2
	s_add_u32 s46, s80, s46
	s_addc_u32 s47, s49, s47
	v_mov_b32_e32 v13, v143
	v_mov_b32_e32 v15, v143
	v_mov_b32_e32 v17, v143
	v_mov_b32_e32 v19, v143
	v_mov_b32_e32 v21, v143
	v_lshl_add_u64 v[2:3], s[46:47], 0, v[142:143]
	v_lshl_add_u64 v[48:49], v[2:3], 0, v[12:13]
	v_lshl_add_u64 v[26:27], v[2:3], 0, v[14:15]
	v_lshl_add_u64 v[36:37], v[2:3], 0, v[16:17]
	v_lshl_add_u64 v[40:41], v[2:3], 0, v[18:19]
	v_lshl_add_u64 v[2:3], v[2:3], 0, v[20:21]
	global_load_dwordx4 v[22:25], v[48:49], off nt
	s_nop 0
	global_load_dwordx4 v[26:29], v[26:27], off nt
	s_nop 0
	global_load_dwordx4 v[36:39], v[36:37], off nt
	s_nop 0
	global_load_dwordx4 v[40:43], v[40:41], off nt
	s_nop 0
	global_load_dwordx4 v[44:47], v[2:3], off nt
	v_add_co_u32_e32 v2, vcc, s53, v48
	v_add_u32_e32 v35, v30, v31
	s_nop 0
	v_addc_co_u32_e32 v3, vcc, 0, v49, vcc
	v_add_co_u32_e32 v52, vcc, s79, v48
	v_add_u32_e32 v62, 0x420, v35
	s_nop 0
	v_addc_co_u32_e32 v53, vcc, 0, v49, vcc
	v_add_co_u32_e32 v56, vcc, s33, v48
	v_add_u32_e32 v63, 0x428, v35
	s_nop 0
	v_addc_co_u32_e32 v57, vcc, 0, v49, vcc
	global_load_dwordx4 v[48:51], v[2:3], off nt
	s_nop 0
	global_load_dwordx4 v[52:55], v[52:53], off nt
	s_nop 0
	global_load_dwordx4 v[56:59], v[56:57], off nt
	v_add_u32_e32 v65, 0x840, v35
	v_add_u32_e32 v66, 0x848, v35
	v_add_u32_e32 v67, 0xc60, v35
	v_add_u32_e32 v68, 0xc68, v35
	v_add_u32_e32 v69, 0x1080, v35
	v_add_u32_e32 v70, 0x1088, v35
	v_add_u32_e32 v71, 0x14a0, v35
	v_add_u32_e32 v72, 0x14a8, v35
	v_add_u32_e32 v73, 0x18c0, v35
	v_add_u32_e32 v74, 0x18c8, v35
	v_add_u32_e32 v75, 0x1ce0, v35
	v_add_u32_e32 v76, 0x1ce8, v35
	s_ashr_i32 s49, s48, 31
	v_lshl_add_u64 v[4:5], s[48:49], 2, v[10:11]
	s_lshl_b64 s[80:81], s[48:49], 12
	s_add_u32 s46, s51, s80
	s_addc_u32 s47, s52, s81
	s_lshl_b32 s48, s84, 6
	s_ashr_i32 s49, s48, 31
	s_add_u32 s46, s46, s48
	s_addc_u32 s47, s47, s49
	v_lshl_add_u64 v[2:3], s[46:47], 0, v[144:145]
	v_add_u32_e32 v64, 0x400, v149
	v_lshl_add_u64 v[60:61], v[2:3], 0, v[6:7]
	s_add_i32 s45, s45, s8
	s_add_i32 s43, s43, s37
	s_add_i32 s44, s44, s55
	s_cmpk_lt_i32 s45, 0x5600
	s_waitcnt vmcnt(7)
	ds_write2_b32 v35, v22, v23 offset1:1
	ds_write2_b32 v35, v24, v25 offset0:2 offset1:3
	s_waitcnt vmcnt(6)
	ds_write2_b32 v69, v26, v27 offset1:1
	ds_write2_b32 v70, v28, v29 offset1:1
	s_waitcnt vmcnt(5)
	ds_write2_b32 v71, v36, v37 offset1:1
	ds_write2_b32 v72, v38, v39 offset1:1
	s_waitcnt vmcnt(4)
	ds_write2_b32 v73, v40, v41 offset1:1
	ds_write2_b32 v74, v42, v43 offset1:1
	s_waitcnt vmcnt(3)
	ds_write2_b32 v75, v44, v45 offset1:1
	ds_write2_b32 v76, v46, v47 offset1:1
	s_waitcnt vmcnt(2)
	ds_write2_b32 v62, v48, v49 offset1:1
	ds_write2_b32 v63, v50, v51 offset1:1
	s_waitcnt vmcnt(1)
	ds_write2_b32 v65, v52, v53 offset1:1
	ds_write2_b32 v66, v54, v55 offset1:1
	s_waitcnt vmcnt(0)
	ds_write2_b32 v67, v56, v57 offset1:1
	ds_write2_b32 v68, v58, v59 offset1:1
	s_waitcnt lgkmcnt(0)
	global_load_dword v13, v[4:5], off
	ds_read2_b32 v[26:27], v149 offset1:16
	ds_read2_b32 v[28:29], v149 offset0:33 offset1:49
	ds_read2_b32 v[36:37], v149 offset0:66 offset1:82
	ds_read2_b32 v[38:39], v149 offset0:99 offset1:115
	ds_read2_b32 v[40:41], v149 offset0:132 offset1:148
	ds_read2_b32 v[42:43], v149 offset0:165 offset1:181
	ds_read2_b32 v[44:45], v149 offset0:198 offset1:214
	ds_read2_b32 v[46:47], v149 offset0:231 offset1:247
	ds_read2_b32 v[48:49], v64 offset0:8 offset1:24
	ds_read2_b32 v[50:51], v64 offset0:41 offset1:57
	ds_read2_b32 v[52:53], v64 offset0:74 offset1:90
	ds_read2_b32 v[54:55], v64 offset0:107 offset1:123
	ds_read2_b32 v[56:57], v64 offset0:140 offset1:156
	ds_read2_b32 v[58:59], v64 offset0:173 offset1:189
	ds_read2_b32 v[62:63], v64 offset0:206 offset1:222
	ds_read2_b32 v[64:65], v64 offset0:239 offset1:255
	s_waitcnt lgkmcnt(14)
	v_mov_b32_e32 v22, v26
	v_mov_b32_e32 v24, v28
	s_waitcnt lgkmcnt(10)
	v_mov_b32_e32 v25, v42
	v_mov_b32_e32 v68, v38
	s_waitcnt lgkmcnt(8)
	v_mov_b32_e32 v69, v46
	s_waitcnt lgkmcnt(6)
	v_mov_b32_e32 v72, v50
	s_waitcnt lgkmcnt(2)
	v_mov_b32_e32 v73, v58
	v_mov_b32_e32 v74, v52
	s_waitcnt lgkmcnt(1)
	v_mov_b32_e32 v75, v62
	v_mov_b32_e32 v76, v54
	s_waitcnt lgkmcnt(0)
	v_mov_b32_e32 v77, v64
	v_mov_b32_e32 v23, v40
	v_mov_b32_e32 v66, v36
	v_mov_b32_e32 v67, v44
	v_mov_b32_e32 v70, v48
	v_mov_b32_e32 v71, v56
	v_mov_b32_e32 v40, v27
	v_mov_b32_e32 v42, v29
	v_mov_b32_e32 v44, v37
	v_mov_b32_e32 v46, v39
	v_mov_b32_e32 v56, v49
	v_mov_b32_e32 v58, v51
	v_mov_b32_e32 v62, v53
	v_mov_b32_e32 v64, v55
	s_waitcnt vmcnt(0)
	v_div_scale_f32 v15, s[46:47], v13, v13, s90
	v_rcp_f32_e32 v19, v15
	v_div_scale_f32 v17, vcc, s90, v13, s90
	v_fma_f32 v21, -v15, v19, 1.0
	v_fmac_f32_e32 v19, v21, v19
	v_mul_f32_e32 v21, v17, v19
	v_fma_f32 v26, -v15, v21, v17
	v_fmac_f32_e32 v21, v26, v19
	v_fma_f32 v15, -v15, v21, v17
	v_div_fmas_f32 v15, v15, v19, v21
	v_div_fixup_f32 v15, v15, v13, s90
	v_cmp_lt_f32_e32 vcc, 0, v13
	s_nop 1
	v_cndmask_b32_e32 v26, 0, v15, vcc
	v_pk_fma_f32 v[24:25], v[24:25], v[26:27], s[78:79] op_sel_hi:[1,0,0]
	v_pk_fma_f32 v[68:69], v[68:69], v[26:27], s[78:79] op_sel_hi:[1,0,0]
	v_pk_fma_f32 v[72:73], v[72:73], v[26:27], s[78:79] op_sel_hi:[1,0,0]
	v_pk_fma_f32 v[74:75], v[74:75], v[26:27], s[78:79] op_sel_hi:[1,0,0]
	v_pk_fma_f32 v[76:77], v[76:77], v[26:27], s[78:79] op_sel_hi:[1,0,0]
	v_pk_fma_f32 v[22:23], v[22:23], v[26:27], s[78:79] op_sel_hi:[1,0,0]
	v_pk_fma_f32 v[66:67], v[66:67], v[26:27], s[78:79] op_sel_hi:[1,0,0]
	v_pk_fma_f32 v[70:71], v[70:71], v[26:27], s[78:79] op_sel_hi:[1,0,0]
	v_lshlrev_b32_e32 v13, 8, v25
	v_lshlrev_b32_e32 v15, 8, v24
	v_lshlrev_b32_e32 v21, 24, v69
	v_lshlrev_b32_e32 v24, 24, v68
	v_lshlrev_b32_e32 v25, 8, v73
	v_lshlrev_b32_e32 v26, 8, v72
	v_lshlrev_b32_e32 v28, 16, v75
	v_lshlrev_b32_e32 v35, 16, v74
	v_lshlrev_b32_e32 v36, 24, v77
	v_lshlrev_b32_e32 v38, 24, v76
	v_lshlrev_b32_e32 v17, 16, v67
	v_lshlrev_b32_e32 v19, 16, v66
	v_and_b32_e32 v13, 0xff00, v13
	v_and_b32_e32 v15, 0xff00, v15
	v_or_b32_sdwa v21, v21, v23 dst_sel:DWORD dst_unused:UNUSED_PAD src0_sel:DWORD src1_sel:BYTE_0
	v_or_b32_sdwa v22, v24, v22 dst_sel:DWORD dst_unused:UNUSED_PAD src0_sel:DWORD src1_sel:BYTE_0
	v_and_b32_e32 v23, 0xff00, v25
	v_and_b32_e32 v24, 0xff00, v26
	v_and_b32_e32 v25, 0xff0000, v28
	v_and_b32_e32 v26, 0xff0000, v35
	v_or_b32_sdwa v28, v36, v71 dst_sel:DWORD dst_unused:UNUSED_PAD src0_sel:DWORD src1_sel:BYTE_0
	v_or_b32_sdwa v35, v38, v70 dst_sel:DWORD dst_unused:UNUSED_PAD src0_sel:DWORD src1_sel:BYTE_0
	v_and_b32_e32 v17, 0xff0000, v17
	v_and_b32_e32 v19, 0xff0000, v19
	v_or_b32_e32 v13, v21, v13
	v_or_b32_e32 v15, v22, v15
	v_or_b32_e32 v21, v28, v23
	v_or_b32_e32 v24, v35, v24
	v_or_b32_e32 v23, v13, v17
	v_or_b32_e32 v22, v15, v19
	v_or_b32_e32 v25, v21, v25
	v_or_b32_e32 v24, v24, v26
	global_store_dwordx4 v[60:61], v[22:25], off
	global_load_dword v4, v[4:5], off offset:64
	s_nop 0
	v_lshl_add_u64 v[22:23], v[2:3], 0, v[146:147]
	s_waitcnt vmcnt(0)
	v_div_scale_f32 v2, s[46:47], v4, v4, s90
	v_rcp_f32_e32 v5, v2
	v_div_scale_f32 v3, vcc, s90, v4, s90
	v_fma_f32 v13, -v2, v5, 1.0
	v_fmac_f32_e32 v5, v13, v5
	v_mul_f32_e32 v13, v3, v5
	v_fma_f32 v15, -v2, v13, v3
	v_fmac_f32_e32 v13, v15, v5
	v_fma_f32 v2, -v2, v13, v3
	v_div_fmas_f32 v2, v2, v5, v13
	v_div_fixup_f32 v2, v2, v4, s90
	v_cmp_lt_f32_e32 vcc, 0, v4
	s_nop 1
	v_cndmask_b32_e32 v2, 0, v2, vcc
	v_pk_fma_f32 v[4:5], v[40:41], v[2:3], s[78:79] op_sel_hi:[1,0,0]
	v_pk_fma_f32 v[24:25], v[42:43], v[2:3], s[78:79] op_sel_hi:[1,0,0]
	v_pk_fma_f32 v[26:27], v[44:45], v[2:3], s[78:79] op_sel_hi:[1,0,0]
	v_pk_fma_f32 v[28:29], v[46:47], v[2:3], s[78:79] op_sel_hi:[1,0,0]
	v_pk_fma_f32 v[36:37], v[56:57], v[2:3], s[78:79] op_sel_hi:[1,0,0]
	v_pk_fma_f32 v[38:39], v[58:59], v[2:3], s[78:79] op_sel_hi:[1,0,0]
	v_pk_fma_f32 v[40:41], v[62:63], v[2:3], s[78:79] op_sel_hi:[1,0,0]
	v_pk_fma_f32 v[2:3], v[64:65], v[2:3], s[78:79] op_sel_hi:[1,0,0]
	v_lshlrev_b32_e32 v13, 8, v25
	v_lshlrev_b32_e32 v15, 8, v24
	v_lshlrev_b32_e32 v19, 16, v26
	v_lshlrev_b32_e32 v21, 24, v29
	v_lshlrev_b32_e32 v24, 24, v28
	v_lshlrev_b32_e32 v25, 8, v39
	v_lshlrev_b32_e32 v26, 8, v38
	v_lshlrev_b32_e32 v3, 24, v3
	v_lshlrev_b32_e32 v2, 24, v2
	v_lshlrev_b32_e32 v17, 16, v27
	v_lshlrev_b32_e32 v27, 16, v41
	v_lshlrev_b32_e32 v28, 16, v40
	v_and_b32_e32 v13, 0xff00, v13
	v_and_b32_e32 v15, 0xff00, v15
	v_or_b32_sdwa v5, v21, v5 dst_sel:DWORD dst_unused:UNUSED_PAD src0_sel:DWORD src1_sel:BYTE_0
	v_or_b32_sdwa v4, v24, v4 dst_sel:DWORD dst_unused:UNUSED_PAD src0_sel:DWORD src1_sel:BYTE_0
	v_and_b32_e32 v21, 0xff00, v25
	v_and_b32_e32 v24, 0xff00, v26
	v_or_b32_sdwa v3, v3, v37 dst_sel:DWORD dst_unused:UNUSED_PAD src0_sel:DWORD src1_sel:BYTE_0
	v_or_b32_sdwa v2, v2, v36 dst_sel:DWORD dst_unused:UNUSED_PAD src0_sel:DWORD src1_sel:BYTE_0
	v_and_b32_e32 v17, 0xff0000, v17
	v_and_b32_e32 v19, 0xff0000, v19
	v_and_b32_e32 v25, 0xff0000, v27
	v_and_b32_e32 v26, 0xff0000, v28
	v_or_b32_e32 v5, v5, v13
	v_or_b32_e32 v4, v4, v15
	v_or_b32_e32 v13, v3, v21
	v_or_b32_e32 v15, v2, v24
	v_or_b32_e32 v3, v5, v17
	v_or_b32_e32 v2, v4, v19
	v_or_b32_e32 v5, v13, v25
	v_or_b32_e32 v4, v15, v26
	global_store_dwordx4 v[22:23], v[2:5], off
	s_waitcnt lgkmcnt(0)
	s_cbranch_scc1 .LBB0_65
	s_branch .LBB0_7

.LBB0_164:
	s_andn2_b64 vcc, exec, s[2:3]
	s_cbranch_vccnz .LBB0_166
	s_add_i32 s36, s31, s78
	s_cmp_gt_u32 s36, 0xa5ff
	s_cbranch_scc1 .Lk_CVT_single
	s_add_i32 s4, s31, 0xffff7a00
	s_bfe_u32 s33, s31, 0x30002
	s_and_b32 s0, s4, 0xfffffe00
	s_lshl_b32 s2, s33, 6
	s_or_b32 s0, s2, s0
	s_bfe_u32 s5, s31, 0x40005
	s_lshl_b64 s[2:3], s[0:1], 13
	s_add_u32 s0, s62, s2
	s_addc_u32 s2, s63, s3
	s_lshl_b32 s3, s5, 9
	s_add_u32 s0, s0, s3
	s_addc_u32 s3, s2, 0
	s_and_b32 s34, s16, 0x60
	s_lshl_b32 s2, s34, 2
	s_add_u32 s2, s0, s2
	s_addc_u32 s3, s3, 0
	v_lshl_add_u64 v[98:99], s[2:3], 0, v[142:143]
	v_mov_b32_e32 v57, v143
	v_mov_b32_e32 v59, v143
	v_lshl_add_u64 v[70:71], v[98:99], 0, v[16:17]
	v_lshl_add_u64 v[74:75], v[98:99], 0, v[18:19]
	v_lshl_add_u64 v[78:79], v[98:99], 0, v[20:21]
	v_lshl_add_u64 v[82:83], v[98:99], 0, v[22:23]
	v_lshl_add_u64 v[86:87], v[98:99], 0, v[56:57]
	v_lshl_add_u64 v[90:91], v[98:99], 0, v[58:59]
	global_load_dwordx4 v[70:73], v[70:71], off nt
	s_nop 0
	global_load_dwordx4 v[74:77], v[74:75], off nt
	s_nop 0
	global_load_dwordx4 v[78:81], v[78:79], off nt
	s_nop 0
	global_load_dwordx4 v[82:85], v[82:83], off nt
	s_nop 0
	global_load_dwordx4 v[86:89], v[86:87], off nt
	s_nop 0
	global_load_dwordx4 v[90:93], v[90:91], off nt
	v_mov_b32_e32 v61, v143
	v_lshl_add_u64 v[94:95], v[98:99], 0, v[60:61]
	global_load_dwordx4 v[94:97], v[94:95], off nt
	v_mov_b32_e32 v63, v143
	v_lshl_add_u64 v[98:99], v[98:99], 0, v[62:63]
	global_load_dwordx4 v[98:101], v[98:99], off nt
	s_add_i32 s31, s31, s78
	s_add_i32 s16, s16, s37
	s_add_i32 s17, s17, s18
	s_mov_b32 s69, 0
	s_add_i32 s72, s31, 0xffff7a00
	s_bfe_u32 s79, s31, 0x30002
	s_and_b32 s68, s72, 0xfffffe00
	s_lshl_b32 s70, s79, 6
	s_or_b32 s68, s70, s68
	s_bfe_u32 s73, s31, 0x40005
	s_lshl_b64 s[70:71], s[68:69], 13
	s_add_u32 s68, s62, s70
	s_addc_u32 s70, s63, s71
	s_lshl_b32 s71, s73, 9
	s_add_u32 s68, s68, s71
	s_addc_u32 s71, s70, 0
	s_and_b32 s74, s16, 0x60
	s_lshl_b32 s70, s74, 2
	s_add_u32 s70, s68, s70
	s_addc_u32 s71, s71, 0
	v_lshl_add_u64 v[248:249], s[70:71], 0, v[142:143]
	v_mov_b32_e32 v57, v143
	v_mov_b32_e32 v59, v143
	v_lshl_add_u64 v[220:221], v[248:249], 0, v[16:17]
	v_lshl_add_u64 v[224:225], v[248:249], 0, v[18:19]
	v_lshl_add_u64 v[228:229], v[248:249], 0, v[20:21]
	v_lshl_add_u64 v[232:233], v[248:249], 0, v[22:23]
	v_lshl_add_u64 v[236:237], v[248:249], 0, v[56:57]
	v_lshl_add_u64 v[240:241], v[248:249], 0, v[58:59]
	global_load_dwordx4 v[220:223], v[220:221], off nt
	s_nop 0
	global_load_dwordx4 v[224:227], v[224:225], off nt
	s_nop 0
	global_load_dwordx4 v[228:231], v[228:229], off nt
	s_nop 0
	global_load_dwordx4 v[232:235], v[232:233], off nt
	s_nop 0
	global_load_dwordx4 v[236:239], v[236:237], off nt
	s_nop 0
	global_load_dwordx4 v[240:243], v[240:241], off nt
	v_mov_b32_e32 v61, v143
	v_lshl_add_u64 v[244:245], v[248:249], 0, v[60:61]
	global_load_dwordx4 v[244:247], v[244:245], off nt
	v_mov_b32_e32 v63, v143
	v_lshl_add_u64 v[248:249], v[248:249], 0, v[62:63]
	global_load_dwordx4 v[248:251], v[248:249], off nt
	s_sub_i32 s31, s31, s78
	s_sub_i32 s16, s16, s37
	s_sub_i32 s17, s17, s18
	v_add_u32_e32 v11, 0x420, v173
	v_add_u32_e32 v13, 0x428, v173
	v_add_u32_e32 v15, 0x840, v173
	v_add_u32_e32 v33, 0x848, v173
	v_add_u32_e32 v47, 0xc60, v173
	v_add_u32_e32 v49, 0xc68, v173
	v_add_u32_e32 v51, 0x1080, v173
	v_add_u32_e32 v53, 0x1088, v173
	v_add_u32_e32 v55, 0x14a0, v173
	v_add_u32_e32 v57, 0x14a8, v173
	v_add_u32_e32 v59, 0x18c0, v173
	v_add_u32_e32 v61, 0x18c8, v173
	v_add_u32_e32 v63, 0x1ce0, v173
	v_add_u32_e32 v67, 0x1ce8, v173
	s_lshr_b32 s0, s4, 5
	s_and_b32 s0, s0, 0x7fffff0
	s_or_b32 s0, s0, s5
	s_lshl_b32 s2, s33, 1
	s_mul_i32 s0, s0, 17
	s_add_i32 s0, s0, s2
	s_lshl_b64 s[2:3], s[0:1], 13
	s_add_u32 s0, s14, s2
	s_addc_u32 s3, s15, s3
	s_lshl_b32 s2, s34, 6
	s_add_u32 s2, s0, s2
	v_mov_b32_e32 v65, v143
	s_addc_u32 s3, s3, 0
	v_lshlrev_b32_e32 v102, 1, v14
	v_mov_b32_e32 v103, v143
	v_lshl_add_u64 v[104:105], s[2:3], 0, v[64:65]
	v_lshl_add_u64 v[102:103], v[104:105], 0, v[102:103]
	s_waitcnt vmcnt(15)
	ds_write2_b32 v173, v70, v71 offset1:1
	ds_write2_b32 v173, v72, v73 offset0:2 offset1:3
	s_waitcnt vmcnt(14)
	ds_write2_b32 v11, v74, v75 offset1:1
	ds_write2_b32 v13, v76, v77 offset1:1
	s_waitcnt vmcnt(13)
	ds_write2_b32 v15, v78, v79 offset1:1
	ds_write2_b32 v33, v80, v81 offset1:1
	s_waitcnt vmcnt(12)
	ds_write2_b32 v47, v82, v83 offset1:1
	ds_write2_b32 v49, v84, v85 offset1:1
	s_waitcnt vmcnt(11)
	ds_write2_b32 v51, v86, v87 offset1:1
	ds_write2_b32 v53, v88, v89 offset1:1
	s_waitcnt vmcnt(10)
	ds_write2_b32 v55, v90, v91 offset1:1
	ds_write2_b32 v57, v92, v93 offset1:1
	s_waitcnt vmcnt(9)
	ds_write2_b32 v59, v94, v95 offset1:1
	ds_write2_b32 v61, v96, v97 offset1:1
	s_waitcnt vmcnt(8)
	ds_write2_b32 v63, v98, v99 offset1:1
	ds_write2_b32 v67, v100, v101 offset1:1
	s_waitcnt lgkmcnt(0)
	ds_read2_b32 v[74:75], v7 offset0:33 offset1:41
	ds_read2_b32 v[76:77], v7 offset1:8
	ds_read2_b32 v[78:79], v7 offset0:66 offset1:74
	ds_read2_b32 v[80:81], v7 offset0:99 offset1:107
	ds_read2_b32 v[82:83], v7 offset0:132 offset1:140
	ds_read2_b32 v[84:85], v7 offset0:165 offset1:173
	s_waitcnt lgkmcnt(4)
	v_bfe_u32 v11, v76, 16, 1
	ds_read2_b32 v[86:87], v7 offset0:198 offset1:206
	v_bfe_u32 v13, v74, 16, 1
	v_add3_u32 v11, v76, v11, s19
	ds_read2_b32 v[88:89], v7 offset0:231 offset1:239
	s_waitcnt lgkmcnt(3)
	v_bfe_u32 v47, v82, 16, 1
	v_add3_u32 v13, v74, v13, s19
	v_lshrrev_b32_e32 v11, 16, v11
	v_and_or_b32 v70, v13, s20, v11
	v_add3_u32 v11, v82, v47, s19
	s_waitcnt lgkmcnt(2)
	v_bfe_u32 v13, v84, 16, 1
	v_lshrrev_b32_e32 v11, 16, v11
	v_add3_u32 v13, v84, v13, s19
	v_and_or_b32 v72, v13, s20, v11
	s_waitcnt lgkmcnt(1)
	v_bfe_u32 v11, v86, 16, 1
	v_add3_u32 v11, v86, v11, s19
	s_waitcnt lgkmcnt(0)
	v_bfe_u32 v13, v88, 16, 1
	v_bfe_u32 v15, v78, 16, 1
	v_lshrrev_b32_e32 v11, 16, v11
	v_add3_u32 v13, v88, v13, s19
	v_bfe_u32 v33, v80, 16, 1
	v_add3_u32 v15, v78, v15, s19
	v_and_or_b32 v73, v13, s20, v11
	v_bfe_u32 v11, v77, 16, 1
	v_add3_u32 v33, v80, v33, s19
	v_lshrrev_b32_e32 v15, 16, v15
	v_add3_u32 v11, v77, v11, s19
	v_bfe_u32 v13, v75, 16, 1
	v_and_or_b32 v71, v33, s20, v15
	v_lshl_add_u64 v[90:91], v[102:103], 0, v[24:25]
	v_lshrrev_b32_e32 v11, 16, v11
	v_add3_u32 v13, v75, v13, s19
	global_store_dwordx4 v[90:91], v[70:73], off
	ds_read2_b32 v[74:75], v7 offset0:16 offset1:24
	v_lshl_add_u64 v[76:77], v[102:103], 0, v[26:27]
	v_and_or_b32 v70, v13, s20, v11
	v_bfe_u32 v11, v79, 16, 1
	v_add3_u32 v11, v79, v11, s19
	v_bfe_u32 v13, v81, 16, 1
	v_lshrrev_b32_e32 v11, 16, v11
	v_add3_u32 v13, v81, v13, s19
	v_and_or_b32 v71, v13, s20, v11
	v_bfe_u32 v11, v83, 16, 1
	v_add3_u32 v11, v83, v11, s19
	v_bfe_u32 v13, v85, 16, 1
	v_lshrrev_b32_e32 v11, 16, v11
	v_add3_u32 v13, v85, v13, s19
	v_and_or_b32 v72, v13, s20, v11
	v_bfe_u32 v11, v87, 16, 1
	v_add3_u32 v11, v87, v11, s19
	v_bfe_u32 v13, v89, 16, 1
	v_lshrrev_b32_e32 v11, 16, v11
	v_add3_u32 v13, v89, v13, s19
	v_and_or_b32 v73, v13, s20, v11
	global_store_dwordx4 v[76:77], v[70:73], off
	ds_read2_b32 v[76:77], v7 offset0:49 offset1:57
	ds_read2_b32 v[78:79], v7 offset0:82 offset1:90
	ds_read2_b32 v[80:81], v7 offset0:115 offset1:123
	s_waitcnt lgkmcnt(3)
	v_bfe_u32 v11, v74, 16, 1
	v_add3_u32 v11, v74, v11, s19
	s_waitcnt lgkmcnt(2)
	v_bfe_u32 v13, v76, 16, 1
	ds_read2_b32 v[82:83], v7 offset0:148 offset1:156
	v_lshrrev_b32_e32 v11, 16, v11
	v_add3_u32 v13, v76, v13, s19
	ds_read2_b32 v[84:85], v7 offset0:181 offset1:189
	v_and_or_b32 v70, v13, s20, v11
	s_waitcnt lgkmcnt(3)
	v_bfe_u32 v11, v78, 16, 1
	v_add3_u32 v11, v78, v11, s19
	s_waitcnt lgkmcnt(2)
	v_bfe_u32 v13, v80, 16, 1
	ds_read2_b32 v[86:87], v7 offset0:214 offset1:222
	v_lshrrev_b32_e32 v11, 16, v11
	v_add3_u32 v13, v80, v13, s19
	ds_read2_b32 v[88:89], v7 offset0:247 offset1:255
	v_and_or_b32 v71, v13, s20, v11
	s_waitcnt lgkmcnt(3)
	v_bfe_u32 v11, v82, 16, 1
	v_add3_u32 v11, v82, v11, s19
	s_waitcnt lgkmcnt(2)
	v_bfe_u32 v13, v84, 16, 1
	v_lshrrev_b32_e32 v11, 16, v11
	v_add3_u32 v13, v84, v13, s19
	v_and_or_b32 v72, v13, s20, v11
	s_waitcnt lgkmcnt(1)
	v_bfe_u32 v11, v86, 16, 1
	v_add3_u32 v11, v86, v11, s19
	s_waitcnt lgkmcnt(0)
	v_bfe_u32 v13, v88, 16, 1
	v_lshrrev_b32_e32 v11, 16, v11
	v_add3_u32 v13, v88, v13, s19
	v_and_or_b32 v73, v13, s20, v11
	v_bfe_u32 v11, v75, 16, 1
	v_add3_u32 v11, v75, v11, s19
	v_bfe_u32 v13, v77, 16, 1
	v_lshl_add_u64 v[90:91], v[102:103], 0, v[28:29]
	v_lshrrev_b32_e32 v11, 16, v11
	v_add3_u32 v13, v77, v13, s19
	global_store_dwordx4 v[90:91], v[70:73], off
	v_lshl_add_u64 v[74:75], v[102:103], 0, v[30:31]
	s_nop 0
	v_and_or_b32 v70, v13, s20, v11
	v_bfe_u32 v11, v79, 16, 1
	v_add3_u32 v11, v79, v11, s19
	v_bfe_u32 v13, v81, 16, 1
	v_lshrrev_b32_e32 v11, 16, v11
	v_add3_u32 v13, v81, v13, s19
	v_and_or_b32 v71, v13, s20, v11
	v_bfe_u32 v11, v83, 16, 1
	v_add3_u32 v11, v83, v11, s19
	v_bfe_u32 v13, v85, 16, 1
	v_lshrrev_b32_e32 v11, 16, v11
	v_add3_u32 v13, v85, v13, s19
	v_and_or_b32 v72, v13, s20, v11
	v_bfe_u32 v11, v87, 16, 1
	v_add3_u32 v11, v87, v11, s19
	v_bfe_u32 v13, v89, 16, 1
	v_lshrrev_b32_e32 v11, 16, v11
	v_add3_u32 v13, v89, v13, s19
	v_and_or_b32 v73, v13, s20, v11
	global_store_dwordx4 v[74:75], v[70:73], off
	s_waitcnt lgkmcnt(0)
	s_add_i32 s31, s31, s78
	s_add_i32 s16, s16, s37
	s_add_i32 s17, s17, s18
	s_add_i32 s4, s31, 0xffff7a00
	s_bfe_u32 s33, s31, 0x30002
	s_and_b32 s0, s4, 0xfffffe00
	s_lshl_b32 s2, s33, 6
	s_or_b32 s0, s2, s0
	s_bfe_u32 s5, s31, 0x40005
	s_lshl_b64 s[2:3], s[0:1], 13
	s_add_u32 s0, s62, s2
	s_addc_u32 s2, s63, s3
	s_lshl_b32 s3, s5, 9
	s_add_u32 s0, s0, s3
	s_addc_u32 s3, s2, 0
	s_and_b32 s34, s16, 0x60
	s_lshl_b32 s2, s34, 2
	s_add_u32 s2, s0, s2
	s_addc_u32 s3, s3, 0
	v_lshl_add_u64 v[98:99], s[2:3], 0, v[142:143]
	v_mov_b32_e32 v57, v143
	v_mov_b32_e32 v59, v143
	v_lshl_add_u64 v[70:71], v[98:99], 0, v[16:17]
	v_lshl_add_u64 v[74:75], v[98:99], 0, v[18:19]
	v_lshl_add_u64 v[78:79], v[98:99], 0, v[20:21]
	v_lshl_add_u64 v[82:83], v[98:99], 0, v[22:23]
	v_lshl_add_u64 v[86:87], v[98:99], 0, v[56:57]
	v_lshl_add_u64 v[90:91], v[98:99], 0, v[58:59]
	s_nop 0
	s_nop 0
	s_nop 0
	s_nop 0
	s_nop 0
	v_mov_b32_e32 v61, v143
	v_lshl_add_u64 v[94:95], v[98:99], 0, v[60:61]
	v_mov_b32_e32 v63, v143
	v_lshl_add_u64 v[98:99], v[98:99], 0, v[62:63]
	v_add_u32_e32 v11, 0x420, v173
	v_add_u32_e32 v13, 0x428, v173
	v_add_u32_e32 v15, 0x840, v173
	v_add_u32_e32 v33, 0x848, v173
	v_add_u32_e32 v47, 0xc60, v173
	v_add_u32_e32 v49, 0xc68, v173
	v_add_u32_e32 v51, 0x1080, v173
	v_add_u32_e32 v53, 0x1088, v173
	v_add_u32_e32 v55, 0x14a0, v173
	v_add_u32_e32 v57, 0x14a8, v173
	v_add_u32_e32 v59, 0x18c0, v173
	v_add_u32_e32 v61, 0x18c8, v173
	v_add_u32_e32 v63, 0x1ce0, v173
	v_add_u32_e32 v67, 0x1ce8, v173
	s_lshr_b32 s0, s4, 5
	s_and_b32 s0, s0, 0x7fffff0
	s_or_b32 s0, s0, s5
	s_lshl_b32 s2, s33, 1
	s_mul_i32 s0, s0, 17
	s_add_i32 s0, s0, s2
	s_lshl_b64 s[2:3], s[0:1], 13
	s_add_u32 s0, s14, s2
	s_addc_u32 s3, s15, s3
	s_lshl_b32 s2, s34, 6
	s_add_u32 s2, s0, s2
	v_mov_b32_e32 v65, v143
	s_addc_u32 s3, s3, 0
	v_lshlrev_b32_e32 v102, 1, v14
	v_mov_b32_e32 v103, v143
	v_lshl_add_u64 v[104:105], s[2:3], 0, v[64:65]
	v_lshl_add_u64 v[102:103], v[104:105], 0, v[102:103]
	s_waitcnt vmcnt(11)
	ds_write2_b32 v173, v220, v221 offset1:1
	ds_write2_b32 v173, v222, v223 offset0:2 offset1:3
	s_waitcnt vmcnt(10)
	ds_write2_b32 v11, v224, v225 offset1:1
	ds_write2_b32 v13, v226, v227 offset1:1
	s_waitcnt vmcnt(9)
	ds_write2_b32 v15, v228, v229 offset1:1
	ds_write2_b32 v33, v230, v231 offset1:1
	s_waitcnt vmcnt(8)
	ds_write2_b32 v47, v232, v233 offset1:1
	ds_write2_b32 v49, v234, v235 offset1:1
	s_waitcnt vmcnt(7)
	ds_write2_b32 v51, v236, v237 offset1:1
	ds_write2_b32 v53, v238, v239 offset1:1
	s_waitcnt vmcnt(6)
	ds_write2_b32 v55, v240, v241 offset1:1
	ds_write2_b32 v57, v242, v243 offset1:1
	s_waitcnt vmcnt(5)
	ds_write2_b32 v59, v244, v245 offset1:1
	ds_write2_b32 v61, v246, v247 offset1:1
	s_waitcnt vmcnt(4)
	ds_write2_b32 v63, v248, v249 offset1:1
	ds_write2_b32 v67, v250, v251 offset1:1
	s_waitcnt lgkmcnt(0)
	ds_read2_b32 v[74:75], v7 offset0:33 offset1:41
	ds_read2_b32 v[76:77], v7 offset1:8
	ds_read2_b32 v[78:79], v7 offset0:66 offset1:74
	ds_read2_b32 v[80:81], v7 offset0:99 offset1:107
	ds_read2_b32 v[82:83], v7 offset0:132 offset1:140
	ds_read2_b32 v[84:85], v7 offset0:165 offset1:173
	s_waitcnt lgkmcnt(4)
	v_bfe_u32 v11, v76, 16, 1
	ds_read2_b32 v[86:87], v7 offset0:198 offset1:206
	v_bfe_u32 v13, v74, 16, 1
	v_add3_u32 v11, v76, v11, s19
	ds_read2_b32 v[88:89], v7 offset0:231 offset1:239
	s_waitcnt lgkmcnt(3)
	v_bfe_u32 v47, v82, 16, 1
	v_add3_u32 v13, v74, v13, s19
	v_lshrrev_b32_e32 v11, 16, v11
	v_and_or_b32 v70, v13, s20, v11
	v_add3_u32 v11, v82, v47, s19
	s_waitcnt lgkmcnt(2)
	v_bfe_u32 v13, v84, 16, 1
	v_lshrrev_b32_e32 v11, 16, v11
	v_add3_u32 v13, v84, v13, s19
	v_and_or_b32 v72, v13, s20, v11
	s_waitcnt lgkmcnt(1)
	v_bfe_u32 v11, v86, 16, 1
	v_add3_u32 v11, v86, v11, s19
	s_waitcnt lgkmcnt(0)
	v_bfe_u32 v13, v88, 16, 1
	v_bfe_u32 v15, v78, 16, 1
	v_lshrrev_b32_e32 v11, 16, v11
	v_add3_u32 v13, v88, v13, s19
	v_bfe_u32 v33, v80, 16, 1
	v_add3_u32 v15, v78, v15, s19
	v_and_or_b32 v73, v13, s20, v11
	v_bfe_u32 v11, v77, 16, 1
	v_add3_u32 v33, v80, v33, s19
	v_lshrrev_b32_e32 v15, 16, v15
	v_add3_u32 v11, v77, v11, s19
	v_bfe_u32 v13, v75, 16, 1
	v_and_or_b32 v71, v33, s20, v15
	v_lshl_add_u64 v[90:91], v[102:103], 0, v[24:25]
	v_lshrrev_b32_e32 v11, 16, v11
	v_add3_u32 v13, v75, v13, s19
	global_store_dwordx4 v[90:91], v[70:73], off
	ds_read2_b32 v[74:75], v7 offset0:16 offset1:24
	v_lshl_add_u64 v[76:77], v[102:103], 0, v[26:27]
	v_and_or_b32 v70, v13, s20, v11
	v_bfe_u32 v11, v79, 16, 1
	v_add3_u32 v11, v79, v11, s19
	v_bfe_u32 v13, v81, 16, 1
	v_lshrrev_b32_e32 v11, 16, v11
	v_add3_u32 v13, v81, v13, s19
	v_and_or_b32 v71, v13, s20, v11
	v_bfe_u32 v11, v83, 16, 1
	v_add3_u32 v11, v83, v11, s19
	v_bfe_u32 v13, v85, 16, 1
	v_lshrrev_b32_e32 v11, 16, v11
	v_add3_u32 v13, v85, v13, s19
	v_and_or_b32 v72, v13, s20, v11
	v_bfe_u32 v11, v87, 16, 1
	v_add3_u32 v11, v87, v11, s19
	v_bfe_u32 v13, v89, 16, 1
	v_lshrrev_b32_e32 v11, 16, v11
	v_add3_u32 v13, v89, v13, s19
	v_and_or_b32 v73, v13, s20, v11
	global_store_dwordx4 v[76:77], v[70:73], off
	ds_read2_b32 v[76:77], v7 offset0:49 offset1:57
	ds_read2_b32 v[78:79], v7 offset0:82 offset1:90
	ds_read2_b32 v[80:81], v7 offset0:115 offset1:123
	s_waitcnt lgkmcnt(3)
	v_bfe_u32 v11, v74, 16, 1
	v_add3_u32 v11, v74, v11, s19
	s_waitcnt lgkmcnt(2)
	v_bfe_u32 v13, v76, 16, 1
	ds_read2_b32 v[82:83], v7 offset0:148 offset1:156
	v_lshrrev_b32_e32 v11, 16, v11
	v_add3_u32 v13, v76, v13, s19
	ds_read2_b32 v[84:85], v7 offset0:181 offset1:189
	v_and_or_b32 v70, v13, s20, v11
	s_waitcnt lgkmcnt(3)
	v_bfe_u32 v11, v78, 16, 1
	v_add3_u32 v11, v78, v11, s19
	s_waitcnt lgkmcnt(2)
	v_bfe_u32 v13, v80, 16, 1
	ds_read2_b32 v[86:87], v7 offset0:214 offset1:222
	v_lshrrev_b32_e32 v11, 16, v11
	v_add3_u32 v13, v80, v13, s19
	ds_read2_b32 v[88:89], v7 offset0:247 offset1:255
	v_and_or_b32 v71, v13, s20, v11
	s_waitcnt lgkmcnt(3)
	v_bfe_u32 v11, v82, 16, 1
	v_add3_u32 v11, v82, v11, s19
	s_waitcnt lgkmcnt(2)
	v_bfe_u32 v13, v84, 16, 1
	v_lshrrev_b32_e32 v11, 16, v11
	v_add3_u32 v13, v84, v13, s19
	v_and_or_b32 v72, v13, s20, v11
	s_waitcnt lgkmcnt(1)
	v_bfe_u32 v11, v86, 16, 1
	v_add3_u32 v11, v86, v11, s19
	s_waitcnt lgkmcnt(0)
	v_bfe_u32 v13, v88, 16, 1
	v_lshrrev_b32_e32 v11, 16, v11
	v_add3_u32 v13, v88, v13, s19
	v_and_or_b32 v73, v13, s20, v11
	v_bfe_u32 v11, v75, 16, 1
	v_add3_u32 v11, v75, v11, s19
	v_bfe_u32 v13, v77, 16, 1
	v_lshl_add_u64 v[90:91], v[102:103], 0, v[28:29]
	v_lshrrev_b32_e32 v11, 16, v11
	v_add3_u32 v13, v77, v13, s19
	global_store_dwordx4 v[90:91], v[70:73], off
	v_lshl_add_u64 v[74:75], v[102:103], 0, v[30:31]
	s_nop 0
	v_and_or_b32 v70, v13, s20, v11
	v_bfe_u32 v11, v79, 16, 1
	v_add3_u32 v11, v79, v11, s19
	v_bfe_u32 v13, v81, 16, 1
	v_lshrrev_b32_e32 v11, 16, v11
	v_add3_u32 v13, v81, v13, s19
	v_and_or_b32 v71, v13, s20, v11
	v_bfe_u32 v11, v83, 16, 1
	v_add3_u32 v11, v83, v11, s19
	v_bfe_u32 v13, v85, 16, 1
	v_lshrrev_b32_e32 v11, 16, v11
	v_add3_u32 v13, v85, v13, s19
	v_and_or_b32 v72, v13, s20, v11
	v_bfe_u32 v11, v87, 16, 1
	v_add3_u32 v11, v87, v11, s19
	v_bfe_u32 v13, v89, 16, 1
	v_lshrrev_b32_e32 v11, 16, v11
	v_add3_u32 v13, v89, v13, s19
	v_and_or_b32 v73, v13, s20, v11
	global_store_dwordx4 v[74:75], v[70:73], off
	s_waitcnt lgkmcnt(0)
	s_branch .LBB0_166
.Lk_CVT_single:
	s_add_i32 s4, s31, 0xffff7a00
	s_bfe_u32 s33, s31, 0x30002
	s_and_b32 s0, s4, 0xfffffe00
	s_lshl_b32 s2, s33, 6
	s_or_b32 s0, s2, s0
	s_bfe_u32 s5, s31, 0x40005
	s_lshl_b64 s[2:3], s[0:1], 13
	s_add_u32 s0, s62, s2
	s_addc_u32 s2, s63, s3
	s_lshl_b32 s3, s5, 9
	s_add_u32 s0, s0, s3
	s_addc_u32 s3, s2, 0
	s_and_b32 s34, s16, 0x60
	s_lshl_b32 s2, s34, 2
	s_add_u32 s2, s0, s2
	s_addc_u32 s3, s3, 0
	v_lshl_add_u64 v[98:99], s[2:3], 0, v[142:143]
	v_mov_b32_e32 v57, v143
	v_mov_b32_e32 v59, v143
	v_lshl_add_u64 v[70:71], v[98:99], 0, v[16:17]
	v_lshl_add_u64 v[74:75], v[98:99], 0, v[18:19]
	v_lshl_add_u64 v[78:79], v[98:99], 0, v[20:21]
	v_lshl_add_u64 v[82:83], v[98:99], 0, v[22:23]
	v_lshl_add_u64 v[86:87], v[98:99], 0, v[56:57]
	v_lshl_add_u64 v[90:91], v[98:99], 0, v[58:59]
	global_load_dwordx4 v[70:73], v[70:71], off nt
	s_nop 0
	global_load_dwordx4 v[74:77], v[74:75], off nt
	s_nop 0
	global_load_dwordx4 v[78:81], v[78:79], off nt
	s_nop 0
	global_load_dwordx4 v[82:85], v[82:83], off nt
	s_nop 0
	global_load_dwordx4 v[86:89], v[86:87], off nt
	s_nop 0
	global_load_dwordx4 v[90:93], v[90:91], off nt
	v_mov_b32_e32 v61, v143
	v_lshl_add_u64 v[94:95], v[98:99], 0, v[60:61]
	global_load_dwordx4 v[94:97], v[94:95], off nt
	v_mov_b32_e32 v63, v143
	v_lshl_add_u64 v[98:99], v[98:99], 0, v[62:63]
	global_load_dwordx4 v[98:101], v[98:99], off nt
	v_add_u32_e32 v11, 0x420, v173
	v_add_u32_e32 v13, 0x428, v173
	v_add_u32_e32 v15, 0x840, v173
	v_add_u32_e32 v33, 0x848, v173
	v_add_u32_e32 v47, 0xc60, v173
	v_add_u32_e32 v49, 0xc68, v173
	v_add_u32_e32 v51, 0x1080, v173
	v_add_u32_e32 v53, 0x1088, v173
	v_add_u32_e32 v55, 0x14a0, v173
	v_add_u32_e32 v57, 0x14a8, v173
	v_add_u32_e32 v59, 0x18c0, v173
	v_add_u32_e32 v61, 0x18c8, v173
	v_add_u32_e32 v63, 0x1ce0, v173
	v_add_u32_e32 v67, 0x1ce8, v173
	s_lshr_b32 s0, s4, 5
	s_and_b32 s0, s0, 0x7fffff0
	s_or_b32 s0, s0, s5
	s_lshl_b32 s2, s33, 1
	s_mul_i32 s0, s0, 17
	s_add_i32 s0, s0, s2
	s_lshl_b64 s[2:3], s[0:1], 13
	s_add_u32 s0, s14, s2
	s_addc_u32 s3, s15, s3
	s_lshl_b32 s2, s34, 6
	s_add_u32 s2, s0, s2
	v_mov_b32_e32 v65, v143
	s_addc_u32 s3, s3, 0
	v_lshlrev_b32_e32 v102, 1, v14
	v_mov_b32_e32 v103, v143
	v_lshl_add_u64 v[104:105], s[2:3], 0, v[64:65]
	v_lshl_add_u64 v[102:103], v[104:105], 0, v[102:103]
	s_waitcnt vmcnt(7)
	ds_write2_b32 v173, v70, v71 offset1:1
	ds_write2_b32 v173, v72, v73 offset0:2 offset1:3
	s_waitcnt vmcnt(6)
	ds_write2_b32 v11, v74, v75 offset1:1
	ds_write2_b32 v13, v76, v77 offset1:1
	s_waitcnt vmcnt(5)
	ds_write2_b32 v15, v78, v79 offset1:1
	ds_write2_b32 v33, v80, v81 offset1:1
	s_waitcnt vmcnt(4)
	ds_write2_b32 v47, v82, v83 offset1:1
	ds_write2_b32 v49, v84, v85 offset1:1
	s_waitcnt vmcnt(3)
	ds_write2_b32 v51, v86, v87 offset1:1
	ds_write2_b32 v53, v88, v89 offset1:1
	s_waitcnt vmcnt(2)
	ds_write2_b32 v55, v90, v91 offset1:1
	ds_write2_b32 v57, v92, v93 offset1:1
	s_waitcnt vmcnt(1)
	ds_write2_b32 v59, v94, v95 offset1:1
	ds_write2_b32 v61, v96, v97 offset1:1
	s_waitcnt vmcnt(0)
	ds_write2_b32 v63, v98, v99 offset1:1
	ds_write2_b32 v67, v100, v101 offset1:1
	s_waitcnt lgkmcnt(0)
	ds_read2_b32 v[74:75], v7 offset0:33 offset1:41
	ds_read2_b32 v[76:77], v7 offset1:8
	ds_read2_b32 v[78:79], v7 offset0:66 offset1:74
	ds_read2_b32 v[80:81], v7 offset0:99 offset1:107
	ds_read2_b32 v[82:83], v7 offset0:132 offset1:140
	ds_read2_b32 v[84:85], v7 offset0:165 offset1:173
	s_waitcnt lgkmcnt(4)
	v_bfe_u32 v11, v76, 16, 1
	ds_read2_b32 v[86:87], v7 offset0:198 offset1:206
	v_bfe_u32 v13, v74, 16, 1
	v_add3_u32 v11, v76, v11, s19
	ds_read2_b32 v[88:89], v7 offset0:231 offset1:239
	s_waitcnt lgkmcnt(3)
	v_bfe_u32 v47, v82, 16, 1
	v_add3_u32 v13, v74, v13, s19
	v_lshrrev_b32_e32 v11, 16, v11
	v_and_or_b32 v70, v13, s20, v11
	v_add3_u32 v11, v82, v47, s19
	s_waitcnt lgkmcnt(2)
	v_bfe_u32 v13, v84, 16, 1
	v_lshrrev_b32_e32 v11, 16, v11
	v_add3_u32 v13, v84, v13, s19
	v_and_or_b32 v72, v13, s20, v11
	s_waitcnt lgkmcnt(1)
	v_bfe_u32 v11, v86, 16, 1
	v_add3_u32 v11, v86, v11, s19
	s_waitcnt lgkmcnt(0)
	v_bfe_u32 v13, v88, 16, 1
	v_bfe_u32 v15, v78, 16, 1
	v_lshrrev_b32_e32 v11, 16, v11
	v_add3_u32 v13, v88, v13, s19
	v_bfe_u32 v33, v80, 16, 1
	v_add3_u32 v15, v78, v15, s19
	v_and_or_b32 v73, v13, s20, v11
	v_bfe_u32 v11, v77, 16, 1
	v_add3_u32 v33, v80, v33, s19
	v_lshrrev_b32_e32 v15, 16, v15
	v_add3_u32 v11, v77, v11, s19
	v_bfe_u32 v13, v75, 16, 1
	v_and_or_b32 v71, v33, s20, v15
	v_lshl_add_u64 v[90:91], v[102:103], 0, v[24:25]
	v_lshrrev_b32_e32 v11, 16, v11
	v_add3_u32 v13, v75, v13, s19
	global_store_dwordx4 v[90:91], v[70:73], off
	ds_read2_b32 v[74:75], v7 offset0:16 offset1:24
	v_lshl_add_u64 v[76:77], v[102:103], 0, v[26:27]
	v_and_or_b32 v70, v13, s20, v11
	v_bfe_u32 v11, v79, 16, 1
	v_add3_u32 v11, v79, v11, s19
	v_bfe_u32 v13, v81, 16, 1
	v_lshrrev_b32_e32 v11, 16, v11
	v_add3_u32 v13, v81, v13, s19
	v_and_or_b32 v71, v13, s20, v11
	v_bfe_u32 v11, v83, 16, 1
	v_add3_u32 v11, v83, v11, s19
	v_bfe_u32 v13, v85, 16, 1
	v_lshrrev_b32_e32 v11, 16, v11
	v_add3_u32 v13, v85, v13, s19
	v_and_or_b32 v72, v13, s20, v11
	v_bfe_u32 v11, v87, 16, 1
	v_add3_u32 v11, v87, v11, s19
	v_bfe_u32 v13, v89, 16, 1
	v_lshrrev_b32_e32 v11, 16, v11
	v_add3_u32 v13, v89, v13, s19
	v_and_or_b32 v73, v13, s20, v11
	global_store_dwordx4 v[76:77], v[70:73], off
	ds_read2_b32 v[76:77], v7 offset0:49 offset1:57
	ds_read2_b32 v[78:79], v7 offset0:82 offset1:90
	ds_read2_b32 v[80:81], v7 offset0:115 offset1:123
	s_waitcnt lgkmcnt(3)
	v_bfe_u32 v11, v74, 16, 1
	v_add3_u32 v11, v74, v11, s19
	s_waitcnt lgkmcnt(2)
	v_bfe_u32 v13, v76, 16, 1
	ds_read2_b32 v[82:83], v7 offset0:148 offset1:156
	v_lshrrev_b32_e32 v11, 16, v11
	v_add3_u32 v13, v76, v13, s19
	ds_read2_b32 v[84:85], v7 offset0:181 offset1:189
	v_and_or_b32 v70, v13, s20, v11
	s_waitcnt lgkmcnt(3)
	v_bfe_u32 v11, v78, 16, 1
	v_add3_u32 v11, v78, v11, s19
	s_waitcnt lgkmcnt(2)
	v_bfe_u32 v13, v80, 16, 1
	ds_read2_b32 v[86:87], v7 offset0:214 offset1:222
	v_lshrrev_b32_e32 v11, 16, v11
	v_add3_u32 v13, v80, v13, s19
	ds_read2_b32 v[88:89], v7 offset0:247 offset1:255
	v_and_or_b32 v71, v13, s20, v11
	s_waitcnt lgkmcnt(3)
	v_bfe_u32 v11, v82, 16, 1
	v_add3_u32 v11, v82, v11, s19
	s_waitcnt lgkmcnt(2)
	v_bfe_u32 v13, v84, 16, 1
	v_lshrrev_b32_e32 v11, 16, v11
	v_add3_u32 v13, v84, v13, s19
	v_and_or_b32 v72, v13, s20, v11
	s_waitcnt lgkmcnt(1)
	v_bfe_u32 v11, v86, 16, 1
	v_add3_u32 v11, v86, v11, s19
	s_waitcnt lgkmcnt(0)
	v_bfe_u32 v13, v88, 16, 1
	v_lshrrev_b32_e32 v11, 16, v11
	v_add3_u32 v13, v88, v13, s19
	v_and_or_b32 v73, v13, s20, v11
	v_bfe_u32 v11, v75, 16, 1
	v_add3_u32 v11, v75, v11, s19
	v_bfe_u32 v13, v77, 16, 1
	v_lshl_add_u64 v[90:91], v[102:103], 0, v[28:29]
	v_lshrrev_b32_e32 v11, 16, v11
	v_add3_u32 v13, v77, v13, s19
	global_store_dwordx4 v[90:91], v[70:73], off
	v_lshl_add_u64 v[74:75], v[102:103], 0, v[30:31]
	s_nop 0
	v_and_or_b32 v70, v13, s20, v11
	v_bfe_u32 v11, v79, 16, 1
	v_add3_u32 v11, v79, v11, s19
	v_bfe_u32 v13, v81, 16, 1
	v_lshrrev_b32_e32 v11, 16, v11
	v_add3_u32 v13, v81, v13, s19
	v_and_or_b32 v71, v13, s20, v11
	v_bfe_u32 v11, v83, 16, 1
	v_add3_u32 v11, v83, v11, s19
	v_bfe_u32 v13, v85, 16, 1
	v_lshrrev_b32_e32 v11, 16, v11
	v_add3_u32 v13, v85, v13, s19
	v_and_or_b32 v72, v13, s20, v11
	v_bfe_u32 v11, v87, 16, 1
	v_add3_u32 v11, v87, v11, s19
	v_bfe_u32 v13, v89, 16, 1
	v_lshrrev_b32_e32 v11, 16, v11
	v_add3_u32 v13, v89, v13, s19
	v_and_or_b32 v73, v13, s20, v11
	global_store_dwordx4 v[74:75], v[70:73], off
	s_waitcnt lgkmcnt(0)

.LBB0_167:
	s_andn2_b64 vcc, exec, s[2:3]
	s_cbranch_vccnz .LBB0_169
	s_add_i32 s36, s31, s78
	s_cmp_gt_u32 s36, 0x85ff
	s_cbranch_scc1 .Lk_DN_single
	s_add_i32 s0, s31, 0xffffd000
	s_lshr_b32 s0, s0, 1
	v_readlane_b32 s40, v254, 0
	s_and_b32 s0, s0, 0x7fffffc0
	v_readlane_b32 s41, v254, 1
	v_readlane_b32 s42, v254, 2
	v_readlane_b32 s43, v254, 3
	v_readlane_b32 s44, v254, 4
	v_readlane_b32 s45, v254, 5
	s_and_b32 s4, s31, 0x7f
	s_lshl_b64 s[2:3], s[0:1], 14
	v_readlane_b32 s46, v254, 6
	v_readlane_b32 s47, v254, 7
	s_mov_b64 s[40:41], s[44:45]
	s_add_u32 s2, s40, s2
	s_addc_u32 s3, s41, s3
	s_lshl_b32 s5, s4, 7
	s_add_u32 s2, s2, s5
	s_addc_u32 s3, s3, 0
	v_lshl_add_u64 v[70:71], s[2:3], 0, v[142:143]
	v_lshlrev_b32_e32 v72, 2, v32
	v_mov_b32_e32 v73, v143
	v_lshl_add_u64 v[98:99], v[70:71], 0, v[72:73]
	v_add_co_u32_e32 v74, vcc, s22, v98
	v_add_u32_e32 v11, 0x420, v173
	s_nop 0
	v_addc_co_u32_e32 v75, vcc, 0, v99, vcc
	v_add_co_u32_e32 v78, vcc, s23, v98
	global_load_dwordx4 v[70:73], v[98:99], off nt
	s_nop 0
	global_load_dwordx4 v[74:77], v[74:75], off nt
	v_addc_co_u32_e32 v79, vcc, 0, v99, vcc
	v_add_co_u32_e32 v82, vcc, s24, v98
	v_add_u32_e32 v13, 0x428, v173
	s_nop 0
	v_addc_co_u32_e32 v83, vcc, 0, v99, vcc
	v_add_co_u32_e32 v86, vcc, s25, v98
	global_load_dwordx4 v[78:81], v[78:79], off nt
	s_nop 0
	global_load_dwordx4 v[82:85], v[82:83], off nt
	v_addc_co_u32_e32 v87, vcc, 0, v99, vcc
	v_add_co_u32_e32 v90, vcc, s26, v98
	v_add_u32_e32 v15, 0x840, v173
	s_nop 0
	v_addc_co_u32_e32 v91, vcc, 0, v99, vcc
	global_load_dwordx4 v[86:89], v[86:87], off nt
	s_nop 0
	global_load_dwordx4 v[90:93], v[90:91], off nt
	v_add_co_u32_e32 v94, vcc, s27, v98
	v_add_u32_e32 v33, 0x848, v173
	s_nop 0
	v_addc_co_u32_e32 v95, vcc, 0, v99, vcc
	global_load_dwordx4 v[94:97], v[94:95], off nt
	v_add_co_u32_e32 v98, vcc, s28, v98
	v_add_u32_e32 v47, 0xc60, v173
	s_nop 0
	v_addc_co_u32_e32 v99, vcc, 0, v99, vcc
	global_load_dwordx4 v[98:101], v[98:99], off nt
	s_add_i32 s31, s31, s78
	s_add_i32 s16, s16, s37
	s_add_i32 s17, s17, s18
	s_mov_b32 s69, 0
	s_add_i32 s68, s31, 0xffffd000
	s_lshr_b32 s68, s68, 1
	v_readlane_b32 s82, v254, 0
	s_and_b32 s68, s68, 0x7fffffc0
	v_readlane_b32 s83, v254, 1
	v_readlane_b32 s84, v254, 2
	v_readlane_b32 s85, v254, 3
	v_readlane_b32 s86, v254, 4
	v_readlane_b32 s87, v254, 5
	s_and_b32 s72, s31, 0x7f
	s_lshl_b64 s[70:71], s[68:69], 14
	v_readlane_b32 s90, v254, 6
	v_readlane_b32 s91, v254, 7
	s_mov_b64 s[82:83], s[86:87]
	s_add_u32 s70, s82, s70
	s_addc_u32 s71, s83, s71
	s_lshl_b32 s73, s72, 7
	s_add_u32 s70, s70, s73
	s_addc_u32 s71, s71, 0
	v_lshl_add_u64 v[220:221], s[70:71], 0, v[142:143]
	v_lshlrev_b32_e32 v222, 2, v32
	v_mov_b32_e32 v223, v143
	v_lshl_add_u64 v[248:249], v[220:221], 0, v[222:223]
	v_add_co_u32_e32 v224, vcc, s22, v248
	v_add_u32_e32 v11, 0x420, v173
	s_nop 0
	v_addc_co_u32_e32 v225, vcc, 0, v249, vcc
	v_add_co_u32_e32 v228, vcc, s23, v248
	global_load_dwordx4 v[220:223], v[248:249], off nt
	s_nop 0
	global_load_dwordx4 v[224:227], v[224:225], off nt
	v_addc_co_u32_e32 v229, vcc, 0, v249, vcc
	v_add_co_u32_e32 v232, vcc, s24, v248
	v_add_u32_e32 v13, 0x428, v173
	s_nop 0
	v_addc_co_u32_e32 v233, vcc, 0, v249, vcc
	v_add_co_u32_e32 v236, vcc, s25, v248
	global_load_dwordx4 v[228:231], v[228:229], off nt
	s_nop 0
	global_load_dwordx4 v[232:235], v[232:233], off nt
	v_addc_co_u32_e32 v237, vcc, 0, v249, vcc
	v_add_co_u32_e32 v240, vcc, s26, v248
	v_add_u32_e32 v15, 0x840, v173
	s_nop 0
	v_addc_co_u32_e32 v241, vcc, 0, v249, vcc
	global_load_dwordx4 v[236:239], v[236:237], off nt
	s_nop 0
	global_load_dwordx4 v[240:243], v[240:241], off nt
	v_add_co_u32_e32 v244, vcc, s27, v248
	v_add_u32_e32 v33, 0x848, v173
	s_nop 0
	v_addc_co_u32_e32 v245, vcc, 0, v249, vcc
	global_load_dwordx4 v[244:247], v[244:245], off nt
	v_add_co_u32_e32 v248, vcc, s28, v248
	v_add_u32_e32 v47, 0xc60, v173
	s_nop 0
	v_addc_co_u32_e32 v249, vcc, 0, v249, vcc
	global_load_dwordx4 v[248:251], v[248:249], off nt
	s_sub_i32 s31, s31, s78
	s_sub_i32 s16, s16, s37
	s_sub_i32 s17, s17, s18
	v_add_u32_e32 v49, 0xc68, v173
	v_add_u32_e32 v51, 0x1080, v173
	v_add_u32_e32 v53, 0x1088, v173
	v_add_u32_e32 v55, 0x14a0, v173
	v_add_u32_e32 v57, 0x14a8, v173
	v_add_u32_e32 v59, 0x18c0, v173
	v_add_u32_e32 v61, 0x18c8, v173
	v_add_u32_e32 v63, 0x1ce0, v173
	v_add_u32_e32 v65, 0x1ce8, v173
	v_mov_b32_e32 v102, v143
	v_mov_b32_e32 v103, v143
	v_mov_b32_e32 v104, v143
	v_mov_b32_e32 v105, v143
	s_mul_i32 s4, s4, 0x56000
	s_add_u32 s2, s8, s4
	s_addc_u32 s3, s9, 0
	s_add_u32 s2, s2, s0
	s_addc_u32 s3, s3, 0
	v_lshl_add_u64 v[106:107], s[2:3], 0, v[144:145]
	v_lshl_add_u64 v[106:107], v[106:107], 0, v[34:35]
	s_mov_b64 s[42:43], s[46:47]
	s_waitcnt vmcnt(15)
	ds_write2_b32 v173, v70, v71 offset1:1
	ds_write2_b32 v173, v72, v73 offset0:2 offset1:3
	s_waitcnt vmcnt(14)
	ds_write2_b32 v11, v74, v75 offset1:1
	ds_write2_b32 v13, v76, v77 offset1:1
	s_waitcnt vmcnt(13)
	ds_write2_b32 v15, v78, v79 offset1:1
	ds_write2_b32 v33, v80, v81 offset1:1
	s_waitcnt vmcnt(12)
	ds_write2_b32 v47, v82, v83 offset1:1
	ds_write2_b32 v49, v84, v85 offset1:1
	s_waitcnt vmcnt(11)
	ds_write2_b32 v51, v86, v87 offset1:1
	ds_write2_b32 v53, v88, v89 offset1:1
	s_waitcnt vmcnt(10)
	ds_write2_b32 v55, v90, v91 offset1:1
	ds_write2_b32 v57, v92, v93 offset1:1
	s_waitcnt vmcnt(9)
	ds_write2_b32 v59, v94, v95 offset1:1
	ds_write2_b32 v61, v96, v97 offset1:1
	s_waitcnt vmcnt(8)
	ds_write2_b32 v63, v98, v99 offset1:1
	ds_write2_b32 v65, v100, v101 offset1:1
	s_waitcnt lgkmcnt(0)
	ds_read2_b32 v[70:71], v149 offset1:16
	ds_read2_b32 v[72:73], v149 offset0:33 offset1:49
	ds_read2_b32 v[74:75], v149 offset0:66 offset1:82
	ds_read2_b32 v[76:77], v149 offset0:99 offset1:115
	ds_read2_b32 v[78:79], v149 offset0:132 offset1:148
	ds_read2_b32 v[80:81], v149 offset0:165 offset1:181
	ds_read2_b32 v[82:83], v149 offset0:198 offset1:214
	ds_read2_b32 v[84:85], v149 offset0:231 offset1:247
	s_waitcnt lgkmcnt(7)
	v_mul_f32_e32 v11, 0x44000000, v70
	s_waitcnt lgkmcnt(6)
	v_mul_f32_e32 v13, 0x44000000, v72
	v_med3_f32 v11, v11, s29, v9
	v_med3_f32 v13, v13, s29, v9
	v_cvt_pk_fp8_f32 v102, v11, v13
	s_waitcnt lgkmcnt(5)
	v_mul_f32_e32 v15, 0x44000000, v74
	s_waitcnt lgkmcnt(4)
	v_mul_f32_e32 v33, 0x44000000, v76
	v_med3_f32 v13, v15, s29, v9
	v_med3_f32 v15, v33, s29, v9
	s_waitcnt lgkmcnt(3)
	v_mul_f32_e32 v11, 0x44000000, v78
	v_cvt_pk_fp8_f32 v102, v13, v15 op_sel:[0,0,1]
	s_waitcnt lgkmcnt(2)
	v_mul_f32_e32 v13, 0x44000000, v80
	v_med3_f32 v11, v11, s29, v9
	v_med3_f32 v13, v13, s29, v9
	v_cvt_pk_fp8_f32 v103, v11, v13
	v_add_u32_e32 v11, 0x400, v149
	ds_read2_b32 v[86:87], v11 offset0:8 offset1:24
	ds_read2_b32 v[88:89], v11 offset0:41 offset1:57
	ds_read2_b32 v[90:91], v11 offset0:74 offset1:90
	ds_read2_b32 v[92:93], v11 offset0:107 offset1:123
	s_waitcnt lgkmcnt(5)
	v_mul_f32_e32 v15, 0x44000000, v82
	s_waitcnt lgkmcnt(4)
	v_mul_f32_e32 v33, 0x44000000, v84
	v_med3_f32 v15, v15, s29, v9
	v_med3_f32 v33, v33, s29, v9
	v_cvt_pk_fp8_f32 v103, v15, v33 op_sel:[0,0,1]
	s_waitcnt lgkmcnt(3)
	v_mul_f32_e32 v13, 0x44000000, v86
	s_waitcnt lgkmcnt(2)
	v_mul_f32_e32 v15, 0x44000000, v88
	v_med3_f32 v13, v13, s29, v9
	v_med3_f32 v15, v15, s29, v9
	v_cvt_pk_fp8_f32 v104, v13, v15
	ds_read2_b32 v[94:95], v11 offset0:140 offset1:156
	ds_read2_b32 v[96:97], v11 offset0:173 offset1:189
	ds_read2_b32 v[98:99], v11 offset0:206 offset1:222
	s_waitcnt lgkmcnt(4)
	v_mul_f32_e32 v33, 0x44000000, v90
	s_waitcnt lgkmcnt(3)
	v_mul_f32_e32 v47, 0x44000000, v92
	v_med3_f32 v33, v33, s29, v9
	v_med3_f32 v13, v47, s29, v9
	ds_read2_b32 v[100:101], v11 offset0:239 offset1:255
	v_cvt_pk_fp8_f32 v104, v33, v13 op_sel:[0,0,1]
	s_waitcnt lgkmcnt(3)
	v_mul_f32_e32 v13, 0x44000000, v94
	s_waitcnt lgkmcnt(2)
	v_mul_f32_e32 v15, 0x44000000, v96
	v_med3_f32 v11, v13, s29, v9
	v_med3_f32 v13, v15, s29, v9
	v_cvt_pk_fp8_f32 v105, v11, v13
	s_waitcnt lgkmcnt(1)
	v_mul_f32_e32 v33, 0x44000000, v98
	s_waitcnt lgkmcnt(0)
	v_mul_f32_e32 v11, 0x44000000, v100
	v_med3_f32 v13, v33, s29, v9
	v_med3_f32 v11, v11, s29, v9
	v_cvt_pk_fp8_f32 v105, v13, v11 op_sel:[0,0,1]
	v_mul_f32_e32 v11, 0x44000000, v71
	v_mul_f32_e32 v13, 0x44000000, v73
	v_med3_f32 v11, v11, s29, v9
	v_med3_f32 v13, v13, s29, v9
	v_mov_b32_e32 v70, v143
	v_cvt_pk_fp8_f32 v70, v11, v13
	v_mul_f32_e32 v15, 0x44000000, v75
	v_mul_f32_e32 v11, 0x44000000, v77
	v_med3_f32 v13, v15, s29, v9
	v_med3_f32 v11, v11, s29, v9
	v_cvt_pk_fp8_f32 v70, v13, v11 op_sel:[0,0,1]
	v_mul_f32_e32 v11, 0x44000000, v79
	v_mul_f32_e32 v13, 0x44000000, v81
	v_med3_f32 v11, v11, s29, v9
	v_med3_f32 v13, v13, s29, v9
	v_mov_b32_e32 v71, v143
	v_cvt_pk_fp8_f32 v71, v11, v13
	v_mul_f32_e32 v15, 0x44000000, v83
	v_mul_f32_e32 v11, 0x44000000, v85
	v_med3_f32 v13, v15, s29, v9
	v_med3_f32 v11, v11, s29, v9
	v_cvt_pk_fp8_f32 v71, v13, v11 op_sel:[0,0,1]
	v_mul_f32_e32 v11, 0x44000000, v87
	v_mul_f32_e32 v13, 0x44000000, v89
	v_med3_f32 v11, v11, s29, v9
	v_med3_f32 v13, v13, s29, v9
	v_mov_b32_e32 v72, v143
	v_cvt_pk_fp8_f32 v72, v11, v13
	v_mul_f32_e32 v15, 0x44000000, v91
	v_mul_f32_e32 v11, 0x44000000, v93
	v_med3_f32 v13, v15, s29, v9
	v_med3_f32 v11, v11, s29, v9
	v_cvt_pk_fp8_f32 v72, v13, v11 op_sel:[0,0,1]
	v_mul_f32_e32 v11, 0x44000000, v95
	v_mul_f32_e32 v13, 0x44000000, v97
	v_med3_f32 v11, v11, s29, v9
	v_med3_f32 v13, v13, s29, v9
	v_mov_b32_e32 v73, v143
	v_cvt_pk_fp8_f32 v73, v11, v13
	v_mul_f32_e32 v15, 0x44000000, v99
	v_mul_f32_e32 v11, 0x44000000, v101
	v_med3_f32 v13, v15, s29, v9
	v_med3_f32 v11, v11, s29, v9
	v_cvt_pk_fp8_f32 v73, v13, v11 op_sel:[0,0,1]
	v_add_co_u32_e32 v74, vcc, 0x2b000, v106
	global_store_dwordx4 v[106:107], v[102:105], off
	s_nop 0
	v_addc_co_u32_e32 v75, vcc, 0, v107, vcc
	global_store_dwordx4 v[74:75], v[70:73], off
	s_waitcnt lgkmcnt(0)
	s_add_i32 s31, s31, s78
	s_add_i32 s16, s16, s37
	s_add_i32 s17, s17, s18
	s_add_i32 s0, s31, 0xffffd000
	s_lshr_b32 s0, s0, 1
	v_readlane_b32 s40, v254, 0
	s_and_b32 s0, s0, 0x7fffffc0
	v_readlane_b32 s41, v254, 1
	v_readlane_b32 s42, v254, 2
	v_readlane_b32 s43, v254, 3
	v_readlane_b32 s44, v254, 4
	v_readlane_b32 s45, v254, 5
	s_and_b32 s4, s31, 0x7f
	s_lshl_b64 s[2:3], s[0:1], 14
	v_readlane_b32 s46, v254, 6
	v_readlane_b32 s47, v254, 7
	s_mov_b64 s[40:41], s[44:45]
	s_add_u32 s2, s40, s2
	s_addc_u32 s3, s41, s3
	s_lshl_b32 s5, s4, 7
	s_add_u32 s2, s2, s5
	s_addc_u32 s3, s3, 0
	v_lshl_add_u64 v[70:71], s[2:3], 0, v[142:143]
	v_lshlrev_b32_e32 v72, 2, v32
	v_mov_b32_e32 v73, v143
	v_lshl_add_u64 v[98:99], v[70:71], 0, v[72:73]
	v_add_co_u32_e32 v74, vcc, s22, v98
	v_add_u32_e32 v11, 0x420, v173
	s_nop 0
	v_addc_co_u32_e32 v75, vcc, 0, v99, vcc
	v_add_co_u32_e32 v78, vcc, s23, v98
	s_nop 0
	v_addc_co_u32_e32 v79, vcc, 0, v99, vcc
	v_add_co_u32_e32 v82, vcc, s24, v98
	v_add_u32_e32 v13, 0x428, v173
	s_nop 0
	v_addc_co_u32_e32 v83, vcc, 0, v99, vcc
	v_add_co_u32_e32 v86, vcc, s25, v98
	s_nop 0
	v_addc_co_u32_e32 v87, vcc, 0, v99, vcc
	v_add_co_u32_e32 v90, vcc, s26, v98
	v_add_u32_e32 v15, 0x840, v173
	s_nop 0
	v_addc_co_u32_e32 v91, vcc, 0, v99, vcc
	s_nop 0
	v_add_co_u32_e32 v94, vcc, s27, v98
	v_add_u32_e32 v33, 0x848, v173
	s_nop 0
	v_addc_co_u32_e32 v95, vcc, 0, v99, vcc
	v_add_co_u32_e32 v98, vcc, s28, v98
	v_add_u32_e32 v47, 0xc60, v173
	s_nop 0
	v_addc_co_u32_e32 v99, vcc, 0, v99, vcc
	v_add_u32_e32 v49, 0xc68, v173
	v_add_u32_e32 v51, 0x1080, v173
	v_add_u32_e32 v53, 0x1088, v173
	v_add_u32_e32 v55, 0x14a0, v173
	v_add_u32_e32 v57, 0x14a8, v173
	v_add_u32_e32 v59, 0x18c0, v173
	v_add_u32_e32 v61, 0x18c8, v173
	v_add_u32_e32 v63, 0x1ce0, v173
	v_add_u32_e32 v65, 0x1ce8, v173
	v_mov_b32_e32 v102, v143
	v_mov_b32_e32 v103, v143
	v_mov_b32_e32 v104, v143
	v_mov_b32_e32 v105, v143
	s_mul_i32 s4, s4, 0x56000
	s_add_u32 s2, s8, s4
	s_addc_u32 s3, s9, 0
	s_add_u32 s2, s2, s0
	s_addc_u32 s3, s3, 0
	v_lshl_add_u64 v[106:107], s[2:3], 0, v[144:145]
	v_lshl_add_u64 v[106:107], v[106:107], 0, v[34:35]
	s_mov_b64 s[42:43], s[46:47]
	s_waitcnt vmcnt(9)
	ds_write2_b32 v173, v220, v221 offset1:1
	ds_write2_b32 v173, v222, v223 offset0:2 offset1:3
	s_waitcnt vmcnt(8)
	ds_write2_b32 v11, v224, v225 offset1:1
	ds_write2_b32 v13, v226, v227 offset1:1
	s_waitcnt vmcnt(7)
	ds_write2_b32 v15, v228, v229 offset1:1
	ds_write2_b32 v33, v230, v231 offset1:1
	s_waitcnt vmcnt(6)
	ds_write2_b32 v47, v232, v233 offset1:1
	ds_write2_b32 v49, v234, v235 offset1:1
	s_waitcnt vmcnt(5)
	ds_write2_b32 v51, v236, v237 offset1:1
	ds_write2_b32 v53, v238, v239 offset1:1
	s_waitcnt vmcnt(4)
	ds_write2_b32 v55, v240, v241 offset1:1
	ds_write2_b32 v57, v242, v243 offset1:1
	s_waitcnt vmcnt(3)
	ds_write2_b32 v59, v244, v245 offset1:1
	ds_write2_b32 v61, v246, v247 offset1:1
	s_waitcnt vmcnt(2)
	ds_write2_b32 v63, v248, v249 offset1:1
	ds_write2_b32 v65, v250, v251 offset1:1
	s_waitcnt lgkmcnt(0)
	ds_read2_b32 v[70:71], v149 offset1:16
	ds_read2_b32 v[72:73], v149 offset0:33 offset1:49
	ds_read2_b32 v[74:75], v149 offset0:66 offset1:82
	ds_read2_b32 v[76:77], v149 offset0:99 offset1:115
	ds_read2_b32 v[78:79], v149 offset0:132 offset1:148
	ds_read2_b32 v[80:81], v149 offset0:165 offset1:181
	ds_read2_b32 v[82:83], v149 offset0:198 offset1:214
	ds_read2_b32 v[84:85], v149 offset0:231 offset1:247
	s_waitcnt lgkmcnt(7)
	v_mul_f32_e32 v11, 0x44000000, v70
	s_waitcnt lgkmcnt(6)
	v_mul_f32_e32 v13, 0x44000000, v72
	v_med3_f32 v11, v11, s29, v9
	v_med3_f32 v13, v13, s29, v9
	v_cvt_pk_fp8_f32 v102, v11, v13
	s_waitcnt lgkmcnt(5)
	v_mul_f32_e32 v15, 0x44000000, v74
	s_waitcnt lgkmcnt(4)
	v_mul_f32_e32 v33, 0x44000000, v76
	v_med3_f32 v13, v15, s29, v9
	v_med3_f32 v15, v33, s29, v9
	s_waitcnt lgkmcnt(3)
	v_mul_f32_e32 v11, 0x44000000, v78
	v_cvt_pk_fp8_f32 v102, v13, v15 op_sel:[0,0,1]
	s_waitcnt lgkmcnt(2)
	v_mul_f32_e32 v13, 0x44000000, v80
	v_med3_f32 v11, v11, s29, v9
	v_med3_f32 v13, v13, s29, v9
	v_cvt_pk_fp8_f32 v103, v11, v13
	v_add_u32_e32 v11, 0x400, v149
	ds_read2_b32 v[86:87], v11 offset0:8 offset1:24
	ds_read2_b32 v[88:89], v11 offset0:41 offset1:57
	ds_read2_b32 v[90:91], v11 offset0:74 offset1:90
	ds_read2_b32 v[92:93], v11 offset0:107 offset1:123
	s_waitcnt lgkmcnt(5)
	v_mul_f32_e32 v15, 0x44000000, v82
	s_waitcnt lgkmcnt(4)
	v_mul_f32_e32 v33, 0x44000000, v84
	v_med3_f32 v15, v15, s29, v9
	v_med3_f32 v33, v33, s29, v9
	v_cvt_pk_fp8_f32 v103, v15, v33 op_sel:[0,0,1]
	s_waitcnt lgkmcnt(3)
	v_mul_f32_e32 v13, 0x44000000, v86
	s_waitcnt lgkmcnt(2)
	v_mul_f32_e32 v15, 0x44000000, v88
	v_med3_f32 v13, v13, s29, v9
	v_med3_f32 v15, v15, s29, v9
	v_cvt_pk_fp8_f32 v104, v13, v15
	ds_read2_b32 v[94:95], v11 offset0:140 offset1:156
	ds_read2_b32 v[96:97], v11 offset0:173 offset1:189
	ds_read2_b32 v[98:99], v11 offset0:206 offset1:222
	s_waitcnt lgkmcnt(4)
	v_mul_f32_e32 v33, 0x44000000, v90
	s_waitcnt lgkmcnt(3)
	v_mul_f32_e32 v47, 0x44000000, v92
	v_med3_f32 v33, v33, s29, v9
	v_med3_f32 v13, v47, s29, v9
	ds_read2_b32 v[100:101], v11 offset0:239 offset1:255
	v_cvt_pk_fp8_f32 v104, v33, v13 op_sel:[0,0,1]
	s_waitcnt lgkmcnt(3)
	v_mul_f32_e32 v13, 0x44000000, v94
	s_waitcnt lgkmcnt(2)
	v_mul_f32_e32 v15, 0x44000000, v96
	v_med3_f32 v11, v13, s29, v9
	v_med3_f32 v13, v15, s29, v9
	v_cvt_pk_fp8_f32 v105, v11, v13
	s_waitcnt lgkmcnt(1)
	v_mul_f32_e32 v33, 0x44000000, v98
	s_waitcnt lgkmcnt(0)
	v_mul_f32_e32 v11, 0x44000000, v100
	v_med3_f32 v13, v33, s29, v9
	v_med3_f32 v11, v11, s29, v9
	v_cvt_pk_fp8_f32 v105, v13, v11 op_sel:[0,0,1]
	v_mul_f32_e32 v11, 0x44000000, v71
	v_mul_f32_e32 v13, 0x44000000, v73
	v_med3_f32 v11, v11, s29, v9
	v_med3_f32 v13, v13, s29, v9
	v_mov_b32_e32 v70, v143
	v_cvt_pk_fp8_f32 v70, v11, v13
	v_mul_f32_e32 v15, 0x44000000, v75
	v_mul_f32_e32 v11, 0x44000000, v77
	v_med3_f32 v13, v15, s29, v9
	v_med3_f32 v11, v11, s29, v9
	v_cvt_pk_fp8_f32 v70, v13, v11 op_sel:[0,0,1]
	v_mul_f32_e32 v11, 0x44000000, v79
	v_mul_f32_e32 v13, 0x44000000, v81
	v_med3_f32 v11, v11, s29, v9
	v_med3_f32 v13, v13, s29, v9
	v_mov_b32_e32 v71, v143
	v_cvt_pk_fp8_f32 v71, v11, v13
	v_mul_f32_e32 v15, 0x44000000, v83
	v_mul_f32_e32 v11, 0x44000000, v85
	v_med3_f32 v13, v15, s29, v9
	v_med3_f32 v11, v11, s29, v9
	v_cvt_pk_fp8_f32 v71, v13, v11 op_sel:[0,0,1]
	v_mul_f32_e32 v11, 0x44000000, v87
	v_mul_f32_e32 v13, 0x44000000, v89
	v_med3_f32 v11, v11, s29, v9
	v_med3_f32 v13, v13, s29, v9
	v_mov_b32_e32 v72, v143
	v_cvt_pk_fp8_f32 v72, v11, v13
	v_mul_f32_e32 v15, 0x44000000, v91
	v_mul_f32_e32 v11, 0x44000000, v93
	v_med3_f32 v13, v15, s29, v9
	v_med3_f32 v11, v11, s29, v9
	v_cvt_pk_fp8_f32 v72, v13, v11 op_sel:[0,0,1]
	v_mul_f32_e32 v11, 0x44000000, v95
	v_mul_f32_e32 v13, 0x44000000, v97
	v_med3_f32 v11, v11, s29, v9
	v_med3_f32 v13, v13, s29, v9
	v_mov_b32_e32 v73, v143
	v_cvt_pk_fp8_f32 v73, v11, v13
	v_mul_f32_e32 v15, 0x44000000, v99
	v_mul_f32_e32 v11, 0x44000000, v101
	v_med3_f32 v13, v15, s29, v9
	v_med3_f32 v11, v11, s29, v9
	v_cvt_pk_fp8_f32 v73, v13, v11 op_sel:[0,0,1]
	v_add_co_u32_e32 v74, vcc, 0x2b000, v106
	global_store_dwordx4 v[106:107], v[102:105], off
	s_nop 0
	v_addc_co_u32_e32 v75, vcc, 0, v107, vcc
	global_store_dwordx4 v[74:75], v[70:73], off
	s_waitcnt lgkmcnt(0)
	s_branch .LBB0_169
.Lk_DN_single:
	s_add_i32 s0, s31, 0xffffd000
	s_lshr_b32 s0, s0, 1
	v_readlane_b32 s40, v254, 0
	s_and_b32 s0, s0, 0x7fffffc0
	v_readlane_b32 s41, v254, 1
	v_readlane_b32 s42, v254, 2
	v_readlane_b32 s43, v254, 3
	v_readlane_b32 s44, v254, 4
	v_readlane_b32 s45, v254, 5
	s_and_b32 s4, s31, 0x7f
	s_lshl_b64 s[2:3], s[0:1], 14
	v_readlane_b32 s46, v254, 6
	v_readlane_b32 s47, v254, 7
	s_mov_b64 s[40:41], s[44:45]
	s_add_u32 s2, s40, s2
	s_addc_u32 s3, s41, s3
	s_lshl_b32 s5, s4, 7
	s_add_u32 s2, s2, s5
	s_addc_u32 s3, s3, 0
	v_lshl_add_u64 v[70:71], s[2:3], 0, v[142:143]
	v_lshlrev_b32_e32 v72, 2, v32
	v_mov_b32_e32 v73, v143
	v_lshl_add_u64 v[98:99], v[70:71], 0, v[72:73]
	v_add_co_u32_e32 v74, vcc, s22, v98
	v_add_u32_e32 v11, 0x420, v173
	s_nop 0
	v_addc_co_u32_e32 v75, vcc, 0, v99, vcc
	v_add_co_u32_e32 v78, vcc, s23, v98
	global_load_dwordx4 v[70:73], v[98:99], off nt
	s_nop 0
	global_load_dwordx4 v[74:77], v[74:75], off nt
	v_addc_co_u32_e32 v79, vcc, 0, v99, vcc
	v_add_co_u32_e32 v82, vcc, s24, v98
	v_add_u32_e32 v13, 0x428, v173
	s_nop 0
	v_addc_co_u32_e32 v83, vcc, 0, v99, vcc
	v_add_co_u32_e32 v86, vcc, s25, v98
	global_load_dwordx4 v[78:81], v[78:79], off nt
	s_nop 0
	global_load_dwordx4 v[82:85], v[82:83], off nt
	v_addc_co_u32_e32 v87, vcc, 0, v99, vcc
	v_add_co_u32_e32 v90, vcc, s26, v98
	v_add_u32_e32 v15, 0x840, v173
	s_nop 0
	v_addc_co_u32_e32 v91, vcc, 0, v99, vcc
	global_load_dwordx4 v[86:89], v[86:87], off nt
	s_nop 0
	global_load_dwordx4 v[90:93], v[90:91], off nt
	v_add_co_u32_e32 v94, vcc, s27, v98
	v_add_u32_e32 v33, 0x848, v173
	s_nop 0
	v_addc_co_u32_e32 v95, vcc, 0, v99, vcc
	global_load_dwordx4 v[94:97], v[94:95], off nt
	v_add_co_u32_e32 v98, vcc, s28, v98
	v_add_u32_e32 v47, 0xc60, v173
	s_nop 0
	v_addc_co_u32_e32 v99, vcc, 0, v99, vcc
	global_load_dwordx4 v[98:101], v[98:99], off nt
	v_add_u32_e32 v49, 0xc68, v173
	v_add_u32_e32 v51, 0x1080, v173
	v_add_u32_e32 v53, 0x1088, v173
	v_add_u32_e32 v55, 0x14a0, v173
	v_add_u32_e32 v57, 0x14a8, v173
	v_add_u32_e32 v59, 0x18c0, v173
	v_add_u32_e32 v61, 0x18c8, v173
	v_add_u32_e32 v63, 0x1ce0, v173
	v_add_u32_e32 v65, 0x1ce8, v173
	v_mov_b32_e32 v102, v143
	v_mov_b32_e32 v103, v143
	v_mov_b32_e32 v104, v143
	v_mov_b32_e32 v105, v143
	s_mul_i32 s4, s4, 0x56000
	s_add_u32 s2, s8, s4
	s_addc_u32 s3, s9, 0
	s_add_u32 s2, s2, s0
	s_addc_u32 s3, s3, 0
	v_lshl_add_u64 v[106:107], s[2:3], 0, v[144:145]
	v_lshl_add_u64 v[106:107], v[106:107], 0, v[34:35]
	s_mov_b64 s[42:43], s[46:47]
	s_waitcnt vmcnt(7)
	ds_write2_b32 v173, v70, v71 offset1:1
	ds_write2_b32 v173, v72, v73 offset0:2 offset1:3
	s_waitcnt vmcnt(6)
	ds_write2_b32 v11, v74, v75 offset1:1
	ds_write2_b32 v13, v76, v77 offset1:1
	s_waitcnt vmcnt(5)
	ds_write2_b32 v15, v78, v79 offset1:1
	ds_write2_b32 v33, v80, v81 offset1:1
	s_waitcnt vmcnt(4)
	ds_write2_b32 v47, v82, v83 offset1:1
	ds_write2_b32 v49, v84, v85 offset1:1
	s_waitcnt vmcnt(3)
	ds_write2_b32 v51, v86, v87 offset1:1
	ds_write2_b32 v53, v88, v89 offset1:1
	s_waitcnt vmcnt(2)
	ds_write2_b32 v55, v90, v91 offset1:1
	ds_write2_b32 v57, v92, v93 offset1:1
	s_waitcnt vmcnt(1)
	ds_write2_b32 v59, v94, v95 offset1:1
	ds_write2_b32 v61, v96, v97 offset1:1
	s_waitcnt vmcnt(0)
	ds_write2_b32 v63, v98, v99 offset1:1
	ds_write2_b32 v65, v100, v101 offset1:1
	s_waitcnt lgkmcnt(0)
	ds_read2_b32 v[70:71], v149 offset1:16
	ds_read2_b32 v[72:73], v149 offset0:33 offset1:49
	ds_read2_b32 v[74:75], v149 offset0:66 offset1:82
	ds_read2_b32 v[76:77], v149 offset0:99 offset1:115
	ds_read2_b32 v[78:79], v149 offset0:132 offset1:148
	ds_read2_b32 v[80:81], v149 offset0:165 offset1:181
	ds_read2_b32 v[82:83], v149 offset0:198 offset1:214
	ds_read2_b32 v[84:85], v149 offset0:231 offset1:247
	s_waitcnt lgkmcnt(7)
	v_mul_f32_e32 v11, 0x44000000, v70
	s_waitcnt lgkmcnt(6)
	v_mul_f32_e32 v13, 0x44000000, v72
	v_med3_f32 v11, v11, s29, v9
	v_med3_f32 v13, v13, s29, v9
	v_cvt_pk_fp8_f32 v102, v11, v13
	s_waitcnt lgkmcnt(5)
	v_mul_f32_e32 v15, 0x44000000, v74
	s_waitcnt lgkmcnt(4)
	v_mul_f32_e32 v33, 0x44000000, v76
	v_med3_f32 v13, v15, s29, v9
	v_med3_f32 v15, v33, s29, v9
	s_waitcnt lgkmcnt(3)
	v_mul_f32_e32 v11, 0x44000000, v78
	v_cvt_pk_fp8_f32 v102, v13, v15 op_sel:[0,0,1]
	s_waitcnt lgkmcnt(2)
	v_mul_f32_e32 v13, 0x44000000, v80
	v_med3_f32 v11, v11, s29, v9
	v_med3_f32 v13, v13, s29, v9
	v_cvt_pk_fp8_f32 v103, v11, v13
	v_add_u32_e32 v11, 0x400, v149
	ds_read2_b32 v[86:87], v11 offset0:8 offset1:24
	ds_read2_b32 v[88:89], v11 offset0:41 offset1:57
	ds_read2_b32 v[90:91], v11 offset0:74 offset1:90
	ds_read2_b32 v[92:93], v11 offset0:107 offset1:123
	s_waitcnt lgkmcnt(5)
	v_mul_f32_e32 v15, 0x44000000, v82
	s_waitcnt lgkmcnt(4)
	v_mul_f32_e32 v33, 0x44000000, v84
	v_med3_f32 v15, v15, s29, v9
	v_med3_f32 v33, v33, s29, v9
	v_cvt_pk_fp8_f32 v103, v15, v33 op_sel:[0,0,1]
	s_waitcnt lgkmcnt(3)
	v_mul_f32_e32 v13, 0x44000000, v86
	s_waitcnt lgkmcnt(2)
	v_mul_f32_e32 v15, 0x44000000, v88
	v_med3_f32 v13, v13, s29, v9
	v_med3_f32 v15, v15, s29, v9
	v_cvt_pk_fp8_f32 v104, v13, v15
	ds_read2_b32 v[94:95], v11 offset0:140 offset1:156
	ds_read2_b32 v[96:97], v11 offset0:173 offset1:189
	ds_read2_b32 v[98:99], v11 offset0:206 offset1:222
	s_waitcnt lgkmcnt(4)
	v_mul_f32_e32 v33, 0x44000000, v90
	s_waitcnt lgkmcnt(3)
	v_mul_f32_e32 v47, 0x44000000, v92
	v_med3_f32 v33, v33, s29, v9
	v_med3_f32 v13, v47, s29, v9
	ds_read2_b32 v[100:101], v11 offset0:239 offset1:255
	v_cvt_pk_fp8_f32 v104, v33, v13 op_sel:[0,0,1]
	s_waitcnt lgkmcnt(3)
	v_mul_f32_e32 v13, 0x44000000, v94
	s_waitcnt lgkmcnt(2)
	v_mul_f32_e32 v15, 0x44000000, v96
	v_med3_f32 v11, v13, s29, v9
	v_med3_f32 v13, v15, s29, v9
	v_cvt_pk_fp8_f32 v105, v11, v13
	s_waitcnt lgkmcnt(1)
	v_mul_f32_e32 v33, 0x44000000, v98
	s_waitcnt lgkmcnt(0)
	v_mul_f32_e32 v11, 0x44000000, v100
	v_med3_f32 v13, v33, s29, v9
	v_med3_f32 v11, v11, s29, v9
	v_cvt_pk_fp8_f32 v105, v13, v11 op_sel:[0,0,1]
	v_mul_f32_e32 v11, 0x44000000, v71
	v_mul_f32_e32 v13, 0x44000000, v73
	v_med3_f32 v11, v11, s29, v9
	v_med3_f32 v13, v13, s29, v9
	v_mov_b32_e32 v70, v143
	v_cvt_pk_fp8_f32 v70, v11, v13
	v_mul_f32_e32 v15, 0x44000000, v75
	v_mul_f32_e32 v11, 0x44000000, v77
	v_med3_f32 v13, v15, s29, v9
	v_med3_f32 v11, v11, s29, v9
	v_cvt_pk_fp8_f32 v70, v13, v11 op_sel:[0,0,1]
	v_mul_f32_e32 v11, 0x44000000, v79
	v_mul_f32_e32 v13, 0x44000000, v81
	v_med3_f32 v11, v11, s29, v9
	v_med3_f32 v13, v13, s29, v9
	v_mov_b32_e32 v71, v143
	v_cvt_pk_fp8_f32 v71, v11, v13
	v_mul_f32_e32 v15, 0x44000000, v83
	v_mul_f32_e32 v11, 0x44000000, v85
	v_med3_f32 v13, v15, s29, v9
	v_med3_f32 v11, v11, s29, v9
	v_cvt_pk_fp8_f32 v71, v13, v11 op_sel:[0,0,1]
	v_mul_f32_e32 v11, 0x44000000, v87
	v_mul_f32_e32 v13, 0x44000000, v89
	v_med3_f32 v11, v11, s29, v9
	v_med3_f32 v13, v13, s29, v9
	v_mov_b32_e32 v72, v143
	v_cvt_pk_fp8_f32 v72, v11, v13
	v_mul_f32_e32 v15, 0x44000000, v91
	v_mul_f32_e32 v11, 0x44000000, v93
	v_med3_f32 v13, v15, s29, v9
	v_med3_f32 v11, v11, s29, v9
	v_cvt_pk_fp8_f32 v72, v13, v11 op_sel:[0,0,1]
	v_mul_f32_e32 v11, 0x44000000, v95
	v_mul_f32_e32 v13, 0x44000000, v97
	v_med3_f32 v11, v11, s29, v9
	v_med3_f32 v13, v13, s29, v9
	v_mov_b32_e32 v73, v143
	v_cvt_pk_fp8_f32 v73, v11, v13
	v_mul_f32_e32 v15, 0x44000000, v99
	v_mul_f32_e32 v11, 0x44000000, v101
	v_med3_f32 v13, v15, s29, v9
	v_med3_f32 v11, v11, s29, v9
	v_cvt_pk_fp8_f32 v73, v13, v11 op_sel:[0,0,1]
	v_add_co_u32_e32 v74, vcc, 0x2b000, v106
	global_store_dwordx4 v[106:107], v[102:105], off
	s_nop 0
	v_addc_co_u32_e32 v75, vcc, 0, v107, vcc
	global_store_dwordx4 v[74:75], v[70:73], off
	s_waitcnt lgkmcnt(0)

.LBB0_170:
	s_andn2_b64 vcc, exec, s[2:3]
	s_cbranch_vccnz .LBB0_172
	s_add_i32 s36, s31, s78
	s_cmp_gt_u32 s36, 0x2fff
	s_cbranch_scc1 .Lk_OUT_single
	s_add_i32 s0, s31, 0xfffff000
	s_lshr_b32 s0, s0, 1
	s_and_b32 s0, s0, 0x7fffffc0
	v_readlane_b32 s40, v254, 35
	s_and_b32 s4, s31, 0x7f
	s_lshl_b64 s[2:3], s[0:1], 14
	v_readlane_b32 s54, v254, 49
	v_readlane_b32 s55, v254, 50
	s_add_u32 s2, s54, s2
	s_addc_u32 s3, s55, s3
	s_lshl_b32 s5, s4, 7
	s_add_u32 s2, s2, s5
	s_addc_u32 s3, s3, 0
	v_lshl_add_u64 v[70:71], s[2:3], 0, v[142:143]
	v_lshlrev_b32_e32 v72, 2, v32
	v_mov_b32_e32 v73, v143
	v_lshl_add_u64 v[98:99], v[70:71], 0, v[72:73]
	v_add_co_u32_e32 v74, vcc, s22, v98
	v_add_u32_e32 v11, 0x420, v173
	s_nop 0
	v_addc_co_u32_e32 v75, vcc, 0, v99, vcc
	v_add_co_u32_e32 v78, vcc, s23, v98
	global_load_dwordx4 v[70:73], v[98:99], off nt
	s_nop 0
	global_load_dwordx4 v[74:77], v[74:75], off nt
	v_addc_co_u32_e32 v79, vcc, 0, v99, vcc
	v_add_co_u32_e32 v82, vcc, s24, v98
	v_add_u32_e32 v13, 0x428, v173
	s_nop 0
	v_addc_co_u32_e32 v83, vcc, 0, v99, vcc
	v_add_co_u32_e32 v86, vcc, s25, v98
	global_load_dwordx4 v[78:81], v[78:79], off nt
	s_nop 0
	global_load_dwordx4 v[82:85], v[82:83], off nt
	v_addc_co_u32_e32 v87, vcc, 0, v99, vcc
	v_add_co_u32_e32 v90, vcc, s26, v98
	v_add_u32_e32 v15, 0x840, v173
	s_nop 0
	v_addc_co_u32_e32 v91, vcc, 0, v99, vcc
	global_load_dwordx4 v[86:89], v[86:87], off nt
	s_nop 0
	global_load_dwordx4 v[90:93], v[90:91], off nt
	v_add_co_u32_e32 v94, vcc, s27, v98
	v_add_u32_e32 v33, 0x848, v173
	s_nop 0
	v_addc_co_u32_e32 v95, vcc, 0, v99, vcc
	global_load_dwordx4 v[94:97], v[94:95], off nt
	v_add_co_u32_e32 v98, vcc, s28, v98
	v_add_u32_e32 v47, 0xc60, v173
	s_nop 0
	v_addc_co_u32_e32 v99, vcc, 0, v99, vcc
	global_load_dwordx4 v[98:101], v[98:99], off nt
	s_add_i32 s31, s31, s78
	s_add_i32 s16, s16, s37
	s_add_i32 s17, s17, s18
	s_mov_b32 s69, 0
	s_add_i32 s68, s31, 0xfffff000
	s_lshr_b32 s68, s68, 1
	s_and_b32 s68, s68, 0x7fffffc0
	v_readlane_b32 s82, v254, 35
	s_and_b32 s72, s31, 0x7f
	s_lshl_b64 s[70:71], s[68:69], 14
	v_readlane_b32 s94, v254, 49
	v_readlane_b32 s95, v254, 50
	s_add_u32 s70, s94, s70
	s_addc_u32 s71, s95, s71
	s_lshl_b32 s73, s72, 7
	s_add_u32 s70, s70, s73
	s_addc_u32 s71, s71, 0
	v_lshl_add_u64 v[220:221], s[70:71], 0, v[142:143]
	v_lshlrev_b32_e32 v222, 2, v32
	v_mov_b32_e32 v223, v143
	v_lshl_add_u64 v[248:249], v[220:221], 0, v[222:223]
	v_add_co_u32_e32 v224, vcc, s22, v248
	v_add_u32_e32 v11, 0x420, v173
	s_nop 0
	v_addc_co_u32_e32 v225, vcc, 0, v249, vcc
	v_add_co_u32_e32 v228, vcc, s23, v248
	global_load_dwordx4 v[220:223], v[248:249], off nt
	s_nop 0
	global_load_dwordx4 v[224:227], v[224:225], off nt
	v_addc_co_u32_e32 v229, vcc, 0, v249, vcc
	v_add_co_u32_e32 v232, vcc, s24, v248
	v_add_u32_e32 v13, 0x428, v173
	s_nop 0
	v_addc_co_u32_e32 v233, vcc, 0, v249, vcc
	v_add_co_u32_e32 v236, vcc, s25, v248
	global_load_dwordx4 v[228:231], v[228:229], off nt
	s_nop 0
	global_load_dwordx4 v[232:235], v[232:233], off nt
	v_addc_co_u32_e32 v237, vcc, 0, v249, vcc
	v_add_co_u32_e32 v240, vcc, s26, v248
	v_add_u32_e32 v15, 0x840, v173
	s_nop 0
	v_addc_co_u32_e32 v241, vcc, 0, v249, vcc
	global_load_dwordx4 v[236:239], v[236:237], off nt
	s_nop 0
	global_load_dwordx4 v[240:243], v[240:241], off nt
	v_add_co_u32_e32 v244, vcc, s27, v248
	v_add_u32_e32 v33, 0x848, v173
	s_nop 0
	v_addc_co_u32_e32 v245, vcc, 0, v249, vcc
	global_load_dwordx4 v[244:247], v[244:245], off nt
	v_add_co_u32_e32 v248, vcc, s28, v248
	v_add_u32_e32 v47, 0xc60, v173
	s_nop 0
	v_addc_co_u32_e32 v249, vcc, 0, v249, vcc
	global_load_dwordx4 v[248:251], v[248:249], off nt
	s_sub_i32 s31, s31, s78
	s_sub_i32 s16, s16, s37
	s_sub_i32 s17, s17, s18
	v_add_u32_e32 v49, 0xc68, v173
	v_add_u32_e32 v51, 0x1080, v173
	v_add_u32_e32 v53, 0x1088, v173
	v_add_u32_e32 v55, 0x14a0, v173
	v_add_u32_e32 v57, 0x14a8, v173
	v_add_u32_e32 v59, 0x18c0, v173
	v_add_u32_e32 v61, 0x18c8, v173
	v_add_u32_e32 v63, 0x1ce0, v173
	v_add_u32_e32 v65, 0x1ce8, v173
	v_mov_b32_e32 v102, v143
	v_mov_b32_e32 v103, v143
	v_mov_b32_e32 v104, v143
	v_mov_b32_e32 v105, v143
	s_lshl_b32 s2, s4, 17
	s_add_u32 s2, s6, s2
	s_addc_u32 s3, s7, 0
	s_add_u32 s2, s2, s0
	s_addc_u32 s3, s3, 0
	v_readlane_b32 s41, v254, 36
	v_readlane_b32 s42, v254, 37
	v_readlane_b32 s43, v254, 38
	v_readlane_b32 s44, v254, 39
	v_readlane_b32 s45, v254, 40
	v_readlane_b32 s46, v254, 41
	v_readlane_b32 s47, v254, 42
	v_readlane_b32 s48, v254, 43
	v_readlane_b32 s49, v254, 44
	v_readlane_b32 s50, v254, 45
	v_readlane_b32 s51, v254, 46
	v_readlane_b32 s52, v254, 47
	v_readlane_b32 s53, v254, 48
	s_waitcnt vmcnt(15)
	ds_write2_b32 v173, v70, v71 offset1:1
	ds_write2_b32 v173, v72, v73 offset0:2 offset1:3
	s_waitcnt vmcnt(14)
	ds_write2_b32 v11, v74, v75 offset1:1
	ds_write2_b32 v13, v76, v77 offset1:1
	s_waitcnt vmcnt(13)
	ds_write2_b32 v15, v78, v79 offset1:1
	ds_write2_b32 v33, v80, v81 offset1:1
	s_waitcnt vmcnt(12)
	ds_write2_b32 v47, v82, v83 offset1:1
	ds_write2_b32 v49, v84, v85 offset1:1
	s_waitcnt vmcnt(11)
	ds_write2_b32 v51, v86, v87 offset1:1
	ds_write2_b32 v53, v88, v89 offset1:1
	s_waitcnt vmcnt(10)
	ds_write2_b32 v55, v90, v91 offset1:1
	ds_write2_b32 v57, v92, v93 offset1:1
	s_waitcnt vmcnt(9)
	ds_write2_b32 v59, v94, v95 offset1:1
	ds_write2_b32 v61, v96, v97 offset1:1
	s_waitcnt vmcnt(8)
	ds_write2_b32 v63, v98, v99 offset1:1
	ds_write2_b32 v65, v100, v101 offset1:1
	s_waitcnt lgkmcnt(0)
	ds_read2_b32 v[70:71], v149 offset1:16
	ds_read2_b32 v[72:73], v149 offset0:33 offset1:49
	ds_read2_b32 v[74:75], v149 offset0:66 offset1:82
	ds_read2_b32 v[76:77], v149 offset0:99 offset1:115
	ds_read2_b32 v[80:81], v149 offset0:132 offset1:148
	ds_read2_b32 v[82:83], v149 offset0:165 offset1:181
	ds_read2_b32 v[84:85], v149 offset0:198 offset1:214
	ds_read2_b32 v[86:87], v149 offset0:231 offset1:247
	s_waitcnt lgkmcnt(7)
	v_mul_f32_e32 v11, 0x44000000, v70
	s_waitcnt lgkmcnt(6)
	v_mul_f32_e32 v13, 0x44000000, v72
	v_med3_f32 v11, v11, s29, v9
	v_med3_f32 v13, v13, s29, v9
	v_cvt_pk_fp8_f32 v102, v11, v13
	s_waitcnt lgkmcnt(3)
	v_mul_f32_e32 v11, 0x44000000, v80
	s_waitcnt lgkmcnt(2)
	v_mul_f32_e32 v13, 0x44000000, v82
	v_med3_f32 v11, v11, s29, v9
	v_med3_f32 v13, v13, s29, v9
	v_mul_f32_e32 v15, 0x44000000, v74
	v_mul_f32_e32 v33, 0x44000000, v76
	v_cvt_pk_fp8_f32 v103, v11, v13
	v_add_u32_e32 v11, 0x400, v149
	v_med3_f32 v15, v15, s29, v9
	v_med3_f32 v33, v33, s29, v9
	ds_read2_b32 v[88:89], v11 offset0:8 offset1:24
	ds_read2_b32 v[90:91], v11 offset0:41 offset1:57
	ds_read2_b32 v[92:93], v11 offset0:74 offset1:90
	ds_read2_b32 v[94:95], v11 offset0:107 offset1:123
	v_cvt_pk_fp8_f32 v102, v15, v33 op_sel:[0,0,1]
	s_waitcnt lgkmcnt(5)
	v_mul_f32_e32 v15, 0x44000000, v84
	s_waitcnt lgkmcnt(4)
	v_mul_f32_e32 v33, 0x44000000, v86
	v_med3_f32 v15, v15, s29, v9
	v_med3_f32 v33, v33, s29, v9
	v_cvt_pk_fp8_f32 v103, v15, v33 op_sel:[0,0,1]
	s_waitcnt lgkmcnt(3)
	v_mul_f32_e32 v13, 0x44000000, v88
	s_waitcnt lgkmcnt(2)
	v_mul_f32_e32 v15, 0x44000000, v90
	v_med3_f32 v13, v13, s29, v9
	v_med3_f32 v15, v15, s29, v9
	v_cvt_pk_fp8_f32 v104, v13, v15
	ds_read2_b32 v[96:97], v11 offset0:140 offset1:156
	ds_read2_b32 v[98:99], v11 offset0:173 offset1:189
	ds_read2_b32 v[100:101], v11 offset0:206 offset1:222
	s_waitcnt lgkmcnt(4)
	v_mul_f32_e32 v33, 0x44000000, v92
	s_waitcnt lgkmcnt(3)
	v_mul_f32_e32 v47, 0x44000000, v94
	v_med3_f32 v33, v33, s29, v9
	v_med3_f32 v13, v47, s29, v9
	ds_read2_b32 v[106:107], v11 offset0:239 offset1:255
	v_cvt_pk_fp8_f32 v104, v33, v13 op_sel:[0,0,1]
	s_waitcnt lgkmcnt(3)
	v_mul_f32_e32 v13, 0x44000000, v96
	s_waitcnt lgkmcnt(2)
	v_mul_f32_e32 v15, 0x44000000, v98
	v_med3_f32 v11, v13, s29, v9
	v_med3_f32 v13, v15, s29, v9
	v_cvt_pk_fp8_f32 v105, v11, v13
	s_waitcnt lgkmcnt(1)
	v_mul_f32_e32 v33, 0x44000000, v100
	s_waitcnt lgkmcnt(0)
	v_mul_f32_e32 v11, 0x44000000, v106
	v_med3_f32 v13, v33, s29, v9
	v_med3_f32 v11, v11, s29, v9
	v_cvt_pk_fp8_f32 v105, v13, v11 op_sel:[0,0,1]
	v_mul_f32_e32 v11, 0x44000000, v71
	v_mul_f32_e32 v13, 0x44000000, v73
	v_med3_f32 v11, v11, s29, v9
	v_med3_f32 v13, v13, s29, v9
	v_mov_b32_e32 v70, v143
	v_cvt_pk_fp8_f32 v70, v11, v13
	v_mul_f32_e32 v15, 0x44000000, v75
	v_mul_f32_e32 v11, 0x44000000, v77
	v_med3_f32 v13, v15, s29, v9
	v_med3_f32 v11, v11, s29, v9
	v_cvt_pk_fp8_f32 v70, v13, v11 op_sel:[0,0,1]
	v_mul_f32_e32 v11, 0x44000000, v81
	v_mul_f32_e32 v13, 0x44000000, v83
	v_med3_f32 v11, v11, s29, v9
	v_med3_f32 v13, v13, s29, v9
	v_mov_b32_e32 v71, v143
	v_cvt_pk_fp8_f32 v71, v11, v13
	v_mul_f32_e32 v15, 0x44000000, v85
	v_mul_f32_e32 v11, 0x44000000, v87
	v_med3_f32 v13, v15, s29, v9
	v_med3_f32 v11, v11, s29, v9
	v_cvt_pk_fp8_f32 v71, v13, v11 op_sel:[0,0,1]
	v_mul_f32_e32 v11, 0x44000000, v89
	v_mul_f32_e32 v13, 0x44000000, v91
	v_med3_f32 v11, v11, s29, v9
	v_med3_f32 v13, v13, s29, v9
	v_mov_b32_e32 v72, v143
	v_cvt_pk_fp8_f32 v72, v11, v13
	v_mul_f32_e32 v15, 0x44000000, v93
	v_mul_f32_e32 v11, 0x44000000, v95
	v_med3_f32 v13, v15, s29, v9
	v_med3_f32 v11, v11, s29, v9
	v_cvt_pk_fp8_f32 v72, v13, v11 op_sel:[0,0,1]
	v_mul_f32_e32 v11, 0x44000000, v97
	v_mul_f32_e32 v13, 0x44000000, v99
	v_med3_f32 v11, v11, s29, v9
	v_med3_f32 v13, v13, s29, v9
	v_mov_b32_e32 v73, v143
	v_cvt_pk_fp8_f32 v73, v11, v13
	v_mul_f32_e32 v15, 0x44000000, v101
	v_mul_f32_e32 v11, 0x44000000, v107
	v_med3_f32 v13, v15, s29, v9
	v_med3_f32 v11, v11, s29, v9
	v_cvt_pk_fp8_f32 v73, v13, v11 op_sel:[0,0,1]
	v_lshl_add_u64 v[78:79], s[2:3], 0, v[144:145]
	v_lshl_add_u64 v[74:75], v[78:79], 0, v[36:37]
	global_store_dwordx4 v[74:75], v[102:105], off
	v_lshl_add_u64 v[74:75], v[78:79], 0, v[146:147]
	global_store_dwordx4 v[74:75], v[70:73], off
	s_waitcnt lgkmcnt(0)
	s_add_i32 s31, s31, s78
	s_add_i32 s16, s16, s37
	s_add_i32 s17, s17, s18
	s_add_i32 s0, s31, 0xfffff000
	s_lshr_b32 s0, s0, 1
	s_and_b32 s0, s0, 0x7fffffc0
	v_readlane_b32 s40, v254, 35
	s_and_b32 s4, s31, 0x7f
	s_lshl_b64 s[2:3], s[0:1], 14
	v_readlane_b32 s54, v254, 49
	v_readlane_b32 s55, v254, 50
	s_add_u32 s2, s54, s2
	s_addc_u32 s3, s55, s3
	s_lshl_b32 s5, s4, 7
	s_add_u32 s2, s2, s5
	s_addc_u32 s3, s3, 0
	v_lshl_add_u64 v[70:71], s[2:3], 0, v[142:143]
	v_lshlrev_b32_e32 v72, 2, v32
	v_mov_b32_e32 v73, v143
	v_lshl_add_u64 v[98:99], v[70:71], 0, v[72:73]
	v_add_co_u32_e32 v74, vcc, s22, v98
	v_add_u32_e32 v11, 0x420, v173
	s_nop 0
	v_addc_co_u32_e32 v75, vcc, 0, v99, vcc
	v_add_co_u32_e32 v78, vcc, s23, v98
	s_nop 0
	v_addc_co_u32_e32 v79, vcc, 0, v99, vcc
	v_add_co_u32_e32 v82, vcc, s24, v98
	v_add_u32_e32 v13, 0x428, v173
	s_nop 0
	v_addc_co_u32_e32 v83, vcc, 0, v99, vcc
	v_add_co_u32_e32 v86, vcc, s25, v98
	s_nop 0
	v_addc_co_u32_e32 v87, vcc, 0, v99, vcc
	v_add_co_u32_e32 v90, vcc, s26, v98
	v_add_u32_e32 v15, 0x840, v173
	s_nop 0
	v_addc_co_u32_e32 v91, vcc, 0, v99, vcc
	s_nop 0
	v_add_co_u32_e32 v94, vcc, s27, v98
	v_add_u32_e32 v33, 0x848, v173
	s_nop 0
	v_addc_co_u32_e32 v95, vcc, 0, v99, vcc
	v_add_co_u32_e32 v98, vcc, s28, v98
	v_add_u32_e32 v47, 0xc60, v173
	s_nop 0
	v_addc_co_u32_e32 v99, vcc, 0, v99, vcc
	v_add_u32_e32 v49, 0xc68, v173
	v_add_u32_e32 v51, 0x1080, v173
	v_add_u32_e32 v53, 0x1088, v173
	v_add_u32_e32 v55, 0x14a0, v173
	v_add_u32_e32 v57, 0x14a8, v173
	v_add_u32_e32 v59, 0x18c0, v173
	v_add_u32_e32 v61, 0x18c8, v173
	v_add_u32_e32 v63, 0x1ce0, v173
	v_add_u32_e32 v65, 0x1ce8, v173
	v_mov_b32_e32 v102, v143
	v_mov_b32_e32 v103, v143
	v_mov_b32_e32 v104, v143
	v_mov_b32_e32 v105, v143
	s_lshl_b32 s2, s4, 17
	s_add_u32 s2, s6, s2
	s_addc_u32 s3, s7, 0
	s_add_u32 s2, s2, s0
	s_addc_u32 s3, s3, 0
	v_readlane_b32 s41, v254, 36
	v_readlane_b32 s42, v254, 37
	v_readlane_b32 s43, v254, 38
	v_readlane_b32 s44, v254, 39
	v_readlane_b32 s45, v254, 40
	v_readlane_b32 s46, v254, 41
	v_readlane_b32 s47, v254, 42
	v_readlane_b32 s48, v254, 43
	v_readlane_b32 s49, v254, 44
	v_readlane_b32 s50, v254, 45
	v_readlane_b32 s51, v254, 46
	v_readlane_b32 s52, v254, 47
	v_readlane_b32 s53, v254, 48
	s_waitcnt vmcnt(9)
	ds_write2_b32 v173, v220, v221 offset1:1
	ds_write2_b32 v173, v222, v223 offset0:2 offset1:3
	s_waitcnt vmcnt(8)
	ds_write2_b32 v11, v224, v225 offset1:1
	ds_write2_b32 v13, v226, v227 offset1:1
	s_waitcnt vmcnt(7)
	ds_write2_b32 v15, v228, v229 offset1:1
	ds_write2_b32 v33, v230, v231 offset1:1
	s_waitcnt vmcnt(6)
	ds_write2_b32 v47, v232, v233 offset1:1
	ds_write2_b32 v49, v234, v235 offset1:1
	s_waitcnt vmcnt(5)
	ds_write2_b32 v51, v236, v237 offset1:1
	ds_write2_b32 v53, v238, v239 offset1:1
	s_waitcnt vmcnt(4)
	ds_write2_b32 v55, v240, v241 offset1:1
	ds_write2_b32 v57, v242, v243 offset1:1
	s_waitcnt vmcnt(3)
	ds_write2_b32 v59, v244, v245 offset1:1
	ds_write2_b32 v61, v246, v247 offset1:1
	s_waitcnt vmcnt(2)
	ds_write2_b32 v63, v248, v249 offset1:1
	ds_write2_b32 v65, v250, v251 offset1:1
	s_waitcnt lgkmcnt(0)
	ds_read2_b32 v[70:71], v149 offset1:16
	ds_read2_b32 v[72:73], v149 offset0:33 offset1:49
	ds_read2_b32 v[74:75], v149 offset0:66 offset1:82
	ds_read2_b32 v[76:77], v149 offset0:99 offset1:115
	ds_read2_b32 v[80:81], v149 offset0:132 offset1:148
	ds_read2_b32 v[82:83], v149 offset0:165 offset1:181
	ds_read2_b32 v[84:85], v149 offset0:198 offset1:214
	ds_read2_b32 v[86:87], v149 offset0:231 offset1:247
	s_waitcnt lgkmcnt(7)
	v_mul_f32_e32 v11, 0x44000000, v70
	s_waitcnt lgkmcnt(6)
	v_mul_f32_e32 v13, 0x44000000, v72
	v_med3_f32 v11, v11, s29, v9
	v_med3_f32 v13, v13, s29, v9
	v_cvt_pk_fp8_f32 v102, v11, v13
	s_waitcnt lgkmcnt(3)
	v_mul_f32_e32 v11, 0x44000000, v80
	s_waitcnt lgkmcnt(2)
	v_mul_f32_e32 v13, 0x44000000, v82
	v_med3_f32 v11, v11, s29, v9
	v_med3_f32 v13, v13, s29, v9
	v_mul_f32_e32 v15, 0x44000000, v74
	v_mul_f32_e32 v33, 0x44000000, v76
	v_cvt_pk_fp8_f32 v103, v11, v13
	v_add_u32_e32 v11, 0x400, v149
	v_med3_f32 v15, v15, s29, v9
	v_med3_f32 v33, v33, s29, v9
	ds_read2_b32 v[88:89], v11 offset0:8 offset1:24
	ds_read2_b32 v[90:91], v11 offset0:41 offset1:57
	ds_read2_b32 v[92:93], v11 offset0:74 offset1:90
	ds_read2_b32 v[94:95], v11 offset0:107 offset1:123
	v_cvt_pk_fp8_f32 v102, v15, v33 op_sel:[0,0,1]
	s_waitcnt lgkmcnt(5)
	v_mul_f32_e32 v15, 0x44000000, v84
	s_waitcnt lgkmcnt(4)
	v_mul_f32_e32 v33, 0x44000000, v86
	v_med3_f32 v15, v15, s29, v9
	v_med3_f32 v33, v33, s29, v9
	v_cvt_pk_fp8_f32 v103, v15, v33 op_sel:[0,0,1]
	s_waitcnt lgkmcnt(3)
	v_mul_f32_e32 v13, 0x44000000, v88
	s_waitcnt lgkmcnt(2)
	v_mul_f32_e32 v15, 0x44000000, v90
	v_med3_f32 v13, v13, s29, v9
	v_med3_f32 v15, v15, s29, v9
	v_cvt_pk_fp8_f32 v104, v13, v15
	ds_read2_b32 v[96:97], v11 offset0:140 offset1:156
	ds_read2_b32 v[98:99], v11 offset0:173 offset1:189
	ds_read2_b32 v[100:101], v11 offset0:206 offset1:222
	s_waitcnt lgkmcnt(4)
	v_mul_f32_e32 v33, 0x44000000, v92
	s_waitcnt lgkmcnt(3)
	v_mul_f32_e32 v47, 0x44000000, v94
	v_med3_f32 v33, v33, s29, v9
	v_med3_f32 v13, v47, s29, v9
	ds_read2_b32 v[106:107], v11 offset0:239 offset1:255
	v_cvt_pk_fp8_f32 v104, v33, v13 op_sel:[0,0,1]
	s_waitcnt lgkmcnt(3)
	v_mul_f32_e32 v13, 0x44000000, v96
	s_waitcnt lgkmcnt(2)
	v_mul_f32_e32 v15, 0x44000000, v98
	v_med3_f32 v11, v13, s29, v9
	v_med3_f32 v13, v15, s29, v9
	v_cvt_pk_fp8_f32 v105, v11, v13
	s_waitcnt lgkmcnt(1)
	v_mul_f32_e32 v33, 0x44000000, v100
	s_waitcnt lgkmcnt(0)
	v_mul_f32_e32 v11, 0x44000000, v106
	v_med3_f32 v13, v33, s29, v9
	v_med3_f32 v11, v11, s29, v9
	v_cvt_pk_fp8_f32 v105, v13, v11 op_sel:[0,0,1]
	v_mul_f32_e32 v11, 0x44000000, v71
	v_mul_f32_e32 v13, 0x44000000, v73
	v_med3_f32 v11, v11, s29, v9
	v_med3_f32 v13, v13, s29, v9
	v_mov_b32_e32 v70, v143
	v_cvt_pk_fp8_f32 v70, v11, v13
	v_mul_f32_e32 v15, 0x44000000, v75
	v_mul_f32_e32 v11, 0x44000000, v77
	v_med3_f32 v13, v15, s29, v9
	v_med3_f32 v11, v11, s29, v9
	v_cvt_pk_fp8_f32 v70, v13, v11 op_sel:[0,0,1]
	v_mul_f32_e32 v11, 0x44000000, v81
	v_mul_f32_e32 v13, 0x44000000, v83
	v_med3_f32 v11, v11, s29, v9
	v_med3_f32 v13, v13, s29, v9
	v_mov_b32_e32 v71, v143
	v_cvt_pk_fp8_f32 v71, v11, v13
	v_mul_f32_e32 v15, 0x44000000, v85
	v_mul_f32_e32 v11, 0x44000000, v87
	v_med3_f32 v13, v15, s29, v9
	v_med3_f32 v11, v11, s29, v9
	v_cvt_pk_fp8_f32 v71, v13, v11 op_sel:[0,0,1]
	v_mul_f32_e32 v11, 0x44000000, v89
	v_mul_f32_e32 v13, 0x44000000, v91
	v_med3_f32 v11, v11, s29, v9
	v_med3_f32 v13, v13, s29, v9
	v_mov_b32_e32 v72, v143
	v_cvt_pk_fp8_f32 v72, v11, v13
	v_mul_f32_e32 v15, 0x44000000, v93
	v_mul_f32_e32 v11, 0x44000000, v95
	v_med3_f32 v13, v15, s29, v9
	v_med3_f32 v11, v11, s29, v9
	v_cvt_pk_fp8_f32 v72, v13, v11 op_sel:[0,0,1]
	v_mul_f32_e32 v11, 0x44000000, v97
	v_mul_f32_e32 v13, 0x44000000, v99
	v_med3_f32 v11, v11, s29, v9
	v_med3_f32 v13, v13, s29, v9
	v_mov_b32_e32 v73, v143
	v_cvt_pk_fp8_f32 v73, v11, v13
	v_mul_f32_e32 v15, 0x44000000, v101
	v_mul_f32_e32 v11, 0x44000000, v107
	v_med3_f32 v13, v15, s29, v9
	v_med3_f32 v11, v11, s29, v9
	v_cvt_pk_fp8_f32 v73, v13, v11 op_sel:[0,0,1]
	v_lshl_add_u64 v[78:79], s[2:3], 0, v[144:145]
	v_lshl_add_u64 v[74:75], v[78:79], 0, v[36:37]
	global_store_dwordx4 v[74:75], v[102:105], off
	v_lshl_add_u64 v[74:75], v[78:79], 0, v[146:147]
	global_store_dwordx4 v[74:75], v[70:73], off
	s_waitcnt lgkmcnt(0)
	s_branch .LBB0_172
.Lk_OUT_single:
	s_add_i32 s0, s31, 0xfffff000
	s_lshr_b32 s0, s0, 1
	s_and_b32 s0, s0, 0x7fffffc0
	v_readlane_b32 s40, v254, 35
	s_and_b32 s4, s31, 0x7f
	s_lshl_b64 s[2:3], s[0:1], 14
	v_readlane_b32 s54, v254, 49
	v_readlane_b32 s55, v254, 50
	s_add_u32 s2, s54, s2
	s_addc_u32 s3, s55, s3
	s_lshl_b32 s5, s4, 7
	s_add_u32 s2, s2, s5
	s_addc_u32 s3, s3, 0
	v_lshl_add_u64 v[70:71], s[2:3], 0, v[142:143]
	v_lshlrev_b32_e32 v72, 2, v32
	v_mov_b32_e32 v73, v143
	v_lshl_add_u64 v[98:99], v[70:71], 0, v[72:73]
	v_add_co_u32_e32 v74, vcc, s22, v98
	v_add_u32_e32 v11, 0x420, v173
	s_nop 0
	v_addc_co_u32_e32 v75, vcc, 0, v99, vcc
	v_add_co_u32_e32 v78, vcc, s23, v98
	global_load_dwordx4 v[70:73], v[98:99], off nt
	s_nop 0
	global_load_dwordx4 v[74:77], v[74:75], off nt
	v_addc_co_u32_e32 v79, vcc, 0, v99, vcc
	v_add_co_u32_e32 v82, vcc, s24, v98
	v_add_u32_e32 v13, 0x428, v173
	s_nop 0
	v_addc_co_u32_e32 v83, vcc, 0, v99, vcc
	v_add_co_u32_e32 v86, vcc, s25, v98
	global_load_dwordx4 v[78:81], v[78:79], off nt
	s_nop 0
	global_load_dwordx4 v[82:85], v[82:83], off nt
	v_addc_co_u32_e32 v87, vcc, 0, v99, vcc
	v_add_co_u32_e32 v90, vcc, s26, v98
	v_add_u32_e32 v15, 0x840, v173
	s_nop 0
	v_addc_co_u32_e32 v91, vcc, 0, v99, vcc
	global_load_dwordx4 v[86:89], v[86:87], off nt
	s_nop 0
	global_load_dwordx4 v[90:93], v[90:91], off nt
	v_add_co_u32_e32 v94, vcc, s27, v98
	v_add_u32_e32 v33, 0x848, v173
	s_nop 0
	v_addc_co_u32_e32 v95, vcc, 0, v99, vcc
	global_load_dwordx4 v[94:97], v[94:95], off nt
	v_add_co_u32_e32 v98, vcc, s28, v98
	v_add_u32_e32 v47, 0xc60, v173
	s_nop 0
	v_addc_co_u32_e32 v99, vcc, 0, v99, vcc
	global_load_dwordx4 v[98:101], v[98:99], off nt
	v_add_u32_e32 v49, 0xc68, v173
	v_add_u32_e32 v51, 0x1080, v173
	v_add_u32_e32 v53, 0x1088, v173
	v_add_u32_e32 v55, 0x14a0, v173
	v_add_u32_e32 v57, 0x14a8, v173
	v_add_u32_e32 v59, 0x18c0, v173
	v_add_u32_e32 v61, 0x18c8, v173
	v_add_u32_e32 v63, 0x1ce0, v173
	v_add_u32_e32 v65, 0x1ce8, v173
	v_mov_b32_e32 v102, v143
	v_mov_b32_e32 v103, v143
	v_mov_b32_e32 v104, v143
	v_mov_b32_e32 v105, v143
	s_lshl_b32 s2, s4, 17
	s_add_u32 s2, s6, s2
	s_addc_u32 s3, s7, 0
	s_add_u32 s2, s2, s0
	s_addc_u32 s3, s3, 0
	v_readlane_b32 s41, v254, 36
	v_readlane_b32 s42, v254, 37
	v_readlane_b32 s43, v254, 38
	v_readlane_b32 s44, v254, 39
	v_readlane_b32 s45, v254, 40
	v_readlane_b32 s46, v254, 41
	v_readlane_b32 s47, v254, 42
	v_readlane_b32 s48, v254, 43
	v_readlane_b32 s49, v254, 44
	v_readlane_b32 s50, v254, 45
	v_readlane_b32 s51, v254, 46
	v_readlane_b32 s52, v254, 47
	v_readlane_b32 s53, v254, 48
	s_waitcnt vmcnt(7)
	ds_write2_b32 v173, v70, v71 offset1:1
	ds_write2_b32 v173, v72, v73 offset0:2 offset1:3
	s_waitcnt vmcnt(6)
	ds_write2_b32 v11, v74, v75 offset1:1
	ds_write2_b32 v13, v76, v77 offset1:1
	s_waitcnt vmcnt(5)
	ds_write2_b32 v15, v78, v79 offset1:1
	ds_write2_b32 v33, v80, v81 offset1:1
	s_waitcnt vmcnt(4)
	ds_write2_b32 v47, v82, v83 offset1:1
	ds_write2_b32 v49, v84, v85 offset1:1
	s_waitcnt vmcnt(3)
	ds_write2_b32 v51, v86, v87 offset1:1
	ds_write2_b32 v53, v88, v89 offset1:1
	s_waitcnt vmcnt(2)
	ds_write2_b32 v55, v90, v91 offset1:1
	ds_write2_b32 v57, v92, v93 offset1:1
	s_waitcnt vmcnt(1)
	ds_write2_b32 v59, v94, v95 offset1:1
	ds_write2_b32 v61, v96, v97 offset1:1
	s_waitcnt vmcnt(0)
	ds_write2_b32 v63, v98, v99 offset1:1
	ds_write2_b32 v65, v100, v101 offset1:1
	s_waitcnt lgkmcnt(0)
	ds_read2_b32 v[70:71], v149 offset1:16
	ds_read2_b32 v[72:73], v149 offset0:33 offset1:49
	ds_read2_b32 v[74:75], v149 offset0:66 offset1:82
	ds_read2_b32 v[76:77], v149 offset0:99 offset1:115
	ds_read2_b32 v[80:81], v149 offset0:132 offset1:148
	ds_read2_b32 v[82:83], v149 offset0:165 offset1:181
	ds_read2_b32 v[84:85], v149 offset0:198 offset1:214
	ds_read2_b32 v[86:87], v149 offset0:231 offset1:247
	s_waitcnt lgkmcnt(7)
	v_mul_f32_e32 v11, 0x44000000, v70
	s_waitcnt lgkmcnt(6)
	v_mul_f32_e32 v13, 0x44000000, v72
	v_med3_f32 v11, v11, s29, v9
	v_med3_f32 v13, v13, s29, v9
	v_cvt_pk_fp8_f32 v102, v11, v13
	s_waitcnt lgkmcnt(3)
	v_mul_f32_e32 v11, 0x44000000, v80
	s_waitcnt lgkmcnt(2)
	v_mul_f32_e32 v13, 0x44000000, v82
	v_med3_f32 v11, v11, s29, v9
	v_med3_f32 v13, v13, s29, v9
	v_mul_f32_e32 v15, 0x44000000, v74
	v_mul_f32_e32 v33, 0x44000000, v76
	v_cvt_pk_fp8_f32 v103, v11, v13
	v_add_u32_e32 v11, 0x400, v149
	v_med3_f32 v15, v15, s29, v9
	v_med3_f32 v33, v33, s29, v9
	ds_read2_b32 v[88:89], v11 offset0:8 offset1:24
	ds_read2_b32 v[90:91], v11 offset0:41 offset1:57
	ds_read2_b32 v[92:93], v11 offset0:74 offset1:90
	ds_read2_b32 v[94:95], v11 offset0:107 offset1:123
	v_cvt_pk_fp8_f32 v102, v15, v33 op_sel:[0,0,1]
	s_waitcnt lgkmcnt(5)
	v_mul_f32_e32 v15, 0x44000000, v84
	s_waitcnt lgkmcnt(4)
	v_mul_f32_e32 v33, 0x44000000, v86
	v_med3_f32 v15, v15, s29, v9
	v_med3_f32 v33, v33, s29, v9
	v_cvt_pk_fp8_f32 v103, v15, v33 op_sel:[0,0,1]
	s_waitcnt lgkmcnt(3)
	v_mul_f32_e32 v13, 0x44000000, v88
	s_waitcnt lgkmcnt(2)
	v_mul_f32_e32 v15, 0x44000000, v90
	v_med3_f32 v13, v13, s29, v9
	v_med3_f32 v15, v15, s29, v9
	v_cvt_pk_fp8_f32 v104, v13, v15
	ds_read2_b32 v[96:97], v11 offset0:140 offset1:156
	ds_read2_b32 v[98:99], v11 offset0:173 offset1:189
	ds_read2_b32 v[100:101], v11 offset0:206 offset1:222
	s_waitcnt lgkmcnt(4)
	v_mul_f32_e32 v33, 0x44000000, v92
	s_waitcnt lgkmcnt(3)
	v_mul_f32_e32 v47, 0x44000000, v94
	v_med3_f32 v33, v33, s29, v9
	v_med3_f32 v13, v47, s29, v9
	ds_read2_b32 v[106:107], v11 offset0:239 offset1:255
	v_cvt_pk_fp8_f32 v104, v33, v13 op_sel:[0,0,1]
	s_waitcnt lgkmcnt(3)
	v_mul_f32_e32 v13, 0x44000000, v96
	s_waitcnt lgkmcnt(2)
	v_mul_f32_e32 v15, 0x44000000, v98
	v_med3_f32 v11, v13, s29, v9
	v_med3_f32 v13, v15, s29, v9
	v_cvt_pk_fp8_f32 v105, v11, v13
	s_waitcnt lgkmcnt(1)
	v_mul_f32_e32 v33, 0x44000000, v100
	s_waitcnt lgkmcnt(0)
	v_mul_f32_e32 v11, 0x44000000, v106
	v_med3_f32 v13, v33, s29, v9
	v_med3_f32 v11, v11, s29, v9
	v_cvt_pk_fp8_f32 v105, v13, v11 op_sel:[0,0,1]
	v_mul_f32_e32 v11, 0x44000000, v71
	v_mul_f32_e32 v13, 0x44000000, v73
	v_med3_f32 v11, v11, s29, v9
	v_med3_f32 v13, v13, s29, v9
	v_mov_b32_e32 v70, v143
	v_cvt_pk_fp8_f32 v70, v11, v13
	v_mul_f32_e32 v15, 0x44000000, v75
	v_mul_f32_e32 v11, 0x44000000, v77
	v_med3_f32 v13, v15, s29, v9
	v_med3_f32 v11, v11, s29, v9
	v_cvt_pk_fp8_f32 v70, v13, v11 op_sel:[0,0,1]
	v_mul_f32_e32 v11, 0x44000000, v81
	v_mul_f32_e32 v13, 0x44000000, v83
	v_med3_f32 v11, v11, s29, v9
	v_med3_f32 v13, v13, s29, v9
	v_mov_b32_e32 v71, v143
	v_cvt_pk_fp8_f32 v71, v11, v13
	v_mul_f32_e32 v15, 0x44000000, v85
	v_mul_f32_e32 v11, 0x44000000, v87
	v_med3_f32 v13, v15, s29, v9
	v_med3_f32 v11, v11, s29, v9
	v_cvt_pk_fp8_f32 v71, v13, v11 op_sel:[0,0,1]
	v_mul_f32_e32 v11, 0x44000000, v89
	v_mul_f32_e32 v13, 0x44000000, v91
	v_med3_f32 v11, v11, s29, v9
	v_med3_f32 v13, v13, s29, v9
	v_mov_b32_e32 v72, v143
	v_cvt_pk_fp8_f32 v72, v11, v13
	v_mul_f32_e32 v15, 0x44000000, v93
	v_mul_f32_e32 v11, 0x44000000, v95
	v_med3_f32 v13, v15, s29, v9
	v_med3_f32 v11, v11, s29, v9
	v_cvt_pk_fp8_f32 v72, v13, v11 op_sel:[0,0,1]
	v_mul_f32_e32 v11, 0x44000000, v97
	v_mul_f32_e32 v13, 0x44000000, v99
	v_med3_f32 v11, v11, s29, v9
	v_med3_f32 v13, v13, s29, v9
	v_mov_b32_e32 v73, v143
	v_cvt_pk_fp8_f32 v73, v11, v13
	v_mul_f32_e32 v15, 0x44000000, v101
	v_mul_f32_e32 v11, 0x44000000, v107
	v_med3_f32 v13, v15, s29, v9
	v_med3_f32 v11, v11, s29, v9
	v_cvt_pk_fp8_f32 v73, v13, v11 op_sel:[0,0,1]
	v_lshl_add_u64 v[78:79], s[2:3], 0, v[144:145]
	v_lshl_add_u64 v[74:75], v[78:79], 0, v[36:37]
	global_store_dwordx4 v[74:75], v[102:105], off
	v_lshl_add_u64 v[74:75], v[78:79], 0, v[146:147]
	global_store_dwordx4 v[74:75], v[70:73], off
	s_waitcnt lgkmcnt(0)
